# wout epilogue (layer>0): bf16 residual loads batched (32 in flight) instead of pairwise load-wait
# speedup vs baseline: 1.0256x; 1.0019x over previous
; #define MFMA(a, b, c) __builtin_amdgcn_mfma_f32_32x32x16_bf16(a, b, c, 0, 0, 0)
; #define ISSUE(k0, bf) do { char* A_ = lw + (bf) * BUF; \
;     _Pragma("unroll") for (int i_ = 0; i_ < 4; ++i_) { glds16(al.ptr(lrow + 32 * i_, (k0) + cg), A_ + i_ * 4096); glds16(bl.ptr(lrow + 32 * i_, (k0) + cg), A_ + ABYTES + i_ * 4096); } \
;     if (HALO) { if (wid == 0) glds16(gh + (k0), A_ + 16384); } } while (0)
; template <bool HALO, class AL, class BL>
; __device__ __forceinline__ void gemm_core(f32x16 (&acc)[2][2], f32x16& hacc, const AL& al, const BL& bl, int K, char* lds,
;                                           const u16* halo0, const u16* halo1, int brow0, int brow1) {
;     ...
;   const int sa = ((wr * 64 + r32) >> 1) & 7, sb0 = ((brow0 + r32) >> 1) & 7, sb1 = ((brow1 + r32) >> 1) & 7, sh = (r32 >> 1) & 7;
;   const int oa = (wr * 64 + r32) * 128, ob0 = ABYTES + (brow0 + r32) * 128, ob1 = ABYTES + (brow1 + r32) * 128, oh = (128 + r32) * 128;
;   __syncthreads();
;   ISSUE(0, 0);
;   const int nk = K >> 6;
;   for (int kt = 0; kt < nk; ++kt) {
;     asm volatile("s_waitcnt vmcnt(0)" ::: "memory");
;     __syncthreads();
;     if (kt + 1 < nk) ISSUE((kt + 1) * 64, (kt + 1) & 1);
;     const char* T = lds + (kt & 1) * BUF;
; #pragma unroll
;     for (int kk = 0; kk < 4; ++kk) {
;       const int c = kk * 2 + hi;
;       bf16x8 a0 = *(const bf16x8*)(T + oa + ((c ^ sa) << 4));
;       bf16x8 a1 = *(const bf16x8*)(T + oa + 4096 + ((c ^ sa) << 4));
;       bf16x8 b0 = *(const bf16x8*)(T + ob0 + ((c ^ sb0) << 4));
;       bf16x8 b1 = *(const bf16x8*)(T + ob1 + ((c ^ sb1) << 4));
;       acc[0][0] = MFMA(a0, b0, acc[0][0]); acc[0][1] = MFMA(a0, b1, acc[0][1]);
;       acc[1][0] = MFMA(a1, b0, acc[1][0]); acc[1][1] = MFMA(a1, b1, acc[1][1]);
;       if (HALO) { bf16x8 ah = *(const bf16x8*)(T + oh + ((c ^ sh) << 4)); hacc = MFMA(ah, b0, hacc); }
;     }
; __device__ __forceinline__ void phase_wout(const P& p, int layer, char* lds) {
;     ...
;   for (int it = 0; tile_at(it, 256, 8, tm, tn); ++it) {
;     f32x16 acc[2][2] = {};
;     LdBf al{ym + (long)tm * 128 * 1024, 1024}, bl{wt + (long)tn * 128 * 1024, 1024};
;     gemm_plain(acc, al, bl, 1024, lds);
.LBB0_240:
	v_readlane_b32 s40, v253, 21
	s_or_b32 s40, s8, s40
	s_lshr_b32 s41, s40, 3
	s_and_b32 s41, s41, 0xf8
	s_lshl_b32 s60, s41, 3
	s_and_b32 s8, s8, 7
	s_sub_i32 s40, s40, s60
	s_or_b32 s8, s41, s8
	s_ashr_i32 s40, s40, 3
	s_lshl_b32 s41, s8, 18
	s_add_u32 s64, s3, s41
	v_mov_b32_e32 v1, v229
	v_mov_b32_e32 v6, v229
	s_addc_u32 s65, s6, 0
	s_ashr_i32 s41, s40, 31
	s_lshl_b64 s[60:61], s[40:41], 18
	v_and_b32_e32 v7, 31, v6
	v_ashrrev_i32_e32 v0, 3, v6
	v_lshrrev_b32_e32 v2, 4, v6
	v_xor_b32_e32 v4, v2, v6
	v_and_or_b32 v10, v1, 64, v7
	v_ashrrev_i32_e32 v1, 31, v0
	s_add_u32 s72, s7, s60
	v_lshlrev_b64 v[0:1], 11, v[0:1]
	v_lshlrev_b32_e32 v4, 4, v4
	s_addc_u32 s73, s18, s61
	v_lshl_add_u64 v[2:3], s[64:65], 0, v[0:1]
	v_and_b32_e32 v200, 0x70, v4
	v_lshl_add_u64 v[64:65], v[2:3], 0, v[200:201]
	v_lshl_add_u64 v[2:3], s[72:73], 0, v[0:1]
	s_mov_b64 s[60:61], 0x10000
	v_lshl_add_u32 v95, v6, 4, 0
	v_lshl_add_u64 v[66:67], v[2:3], 0, v[200:201]
	v_lshl_add_u64 v[2:3], v[0:1], 0, s[60:61]
	v_add_u32_e32 v99, 0x4000, v95
	v_readfirstlane_b32 s85, v95
	v_lshl_add_u64 v[4:5], s[64:65], 0, v[2:3]
	v_lshl_add_u64 v[2:3], s[72:73], 0, v[2:3]
	s_mov_b64 s[60:61], 0x20000
	s_mov_b32 m0, s85
	v_readfirstlane_b32 s92, v99
	v_add_u32_e32 v100, 0x1000, v95
	v_lshl_add_u64 v[70:71], v[2:3], 0, v[200:201]
	v_lshl_add_u64 v[2:3], v[0:1], 0, s[60:61]
	s_barrier
	global_load_lds_dwordx4 v[64:65], off
	s_mov_b32 m0, s92
	v_lshl_add_u64 v[68:69], v[4:5], 0, v[200:201]
	v_readfirstlane_b32 s70, v100
	v_add_u32_e32 v101, 0x5000, v95
	v_lshl_add_u64 v[4:5], s[64:65], 0, v[2:3]
	global_load_lds_dwordx4 v[66:67], off
	s_mov_b32 m0, s70
	v_readfirstlane_b32 s71, v101
	v_lshl_add_u64 v[72:73], v[4:5], 0, v[200:201]
	v_add_u32_e32 v4, 0x2000, v95
	v_lshl_add_u64 v[2:3], s[72:73], 0, v[2:3]
	s_mov_b64 s[80:81], 0x30000
	global_load_lds_dwordx4 v[68:69], off
	s_mov_b32 m0, s71
	v_readfirstlane_b32 s41, v4
	v_lshl_add_u64 v[74:75], v[2:3], 0, v[200:201]
	v_add_u32_e32 v2, 0x6000, v95
	v_lshl_add_u64 v[0:1], v[0:1], 0, s[80:81]
	v_lshrrev_b32_e32 v8, 5, v6
	v_bfe_u32 v11, v6, 1, 3
	global_load_lds_dwordx4 v[70:71], off
	s_mov_b32 m0, s41
	v_readfirstlane_b32 s60, v2
	v_lshl_add_u64 v[2:3], s[64:65], 0, v[0:1]
	v_add_u32_e32 v88, 0x3000, v95
	v_lshl_add_u64 v[0:1], s[72:73], 0, v[0:1]
	global_load_lds_dwordx4 v[72:73], off
	s_mov_b32 m0, s60
	v_readfirstlane_b32 s61, v88
	v_lshl_add_u64 v[78:79], v[0:1], 0, v[200:201]
	v_add_u32_e32 v89, 0x7000, v95
	v_bfe_u32 v0, v6, 5, 1
	v_bitop3_b32 v1, v8, v11, 1 bitop3:0x6c
	global_load_lds_dwordx4 v[74:75], off
	v_lshl_add_u64 v[76:77], v[2:3], 0, v[200:201]
	s_mov_b32 m0, s61
	v_readfirstlane_b32 s63, v89
	v_lshlrev_b32_e32 v8, 4, v1
	v_bitop3_b32 v1, v0, v11, 2 bitop3:0x36
	v_add_u32_e32 v91, 0x8000, v95
	global_load_lds_dwordx4 v[76:77], off
	s_mov_b32 m0, s63
	v_lshlrev_b32_e32 v82, 4, v1
	v_bitop3_b32 v1, v0, v11, 4 bitop3:0x36
	v_bitop3_b32 v0, v0, v11, 6 bitop3:0x36
	v_add_u32_e32 v90, 0xc000, v95
	v_readfirstlane_b32 s69, v91
	global_load_lds_dwordx4 v[78:79], off
	v_lshlrev_b32_e32 v114, 4, v1
	v_lshlrev_b32_e32 v118, 4, v0
	v_lshl_add_u64 v[0:1], v[64:65], 0, s[78:79]
	s_mov_b32 m0, s69
	v_readfirstlane_b32 s72, v90
	v_add_u32_e32 v92, 0x9000, v95
	s_waitcnt vmcnt(0)
	s_waitcnt vmcnt(0) lgkmcnt(0)
	s_barrier
	global_load_lds_dwordx4 v[0:1], off
	v_lshl_add_u64 v[0:1], v[66:67], 0, s[78:79]
	s_mov_b32 m0, s72
	v_readfirstlane_b32 s73, v92
	v_add_u32_e32 v93, 0xd000, v95
	global_load_lds_dwordx4 v[0:1], off
	v_lshl_add_u64 v[0:1], v[68:69], 0, s[78:79]
	s_mov_b32 m0, s73
	v_readfirstlane_b32 s80, v93
	v_add_u32_e32 v94, 0xa000, v95
	global_load_lds_dwordx4 v[0:1], off
	v_lshl_add_u64 v[0:1], v[70:71], 0, s[78:79]
	s_mov_b32 m0, s80
	v_readfirstlane_b32 s81, v94
	v_add_u32_e32 v96, 0xe000, v95
	global_load_lds_dwordx4 v[0:1], off
	v_lshl_add_u64 v[0:1], v[72:73], 0, s[78:79]
	s_mov_b32 m0, s81
	v_readfirstlane_b32 s82, v96
	v_add_u32_e32 v97, 0xb000, v95
	v_lshrrev_b32_e32 v9, 1, v6
	global_load_lds_dwordx4 v[0:1], off
	v_lshl_add_u64 v[0:1], v[74:75], 0, s[78:79]
	s_mov_b32 m0, s82
	v_readfirstlane_b32 s83, v97
	v_add_u32_e32 v98, 0xf000, v95
	v_and_or_b32 v2, v9, s52, v7
	global_load_lds_dwordx4 v[0:1], off
	v_lshl_add_u64 v[0:1], v[76:77], 0, s[78:79]
	s_mov_b32 m0, s83
	v_readfirstlane_b32 s84, v98
	global_load_lds_dwordx4 v[0:1], off
	v_lshl_add_u64 v[0:1], v[78:79], 0, s[78:79]
	s_mov_b32 m0, s84
	v_lshl_add_u32 v119, v2, 7, 0
	v_lshl_add_u32 v120, v10, 7, 0
	global_load_lds_dwordx4 v[0:1], off
	v_add_u32_e32 v80, v119, v8
	v_add_u32_e32 v81, v120, v8
	ds_read_b128 v[0:3], v80
	ds_read_b128 v[4:7], v80 offset:4096
	ds_read_b128 v[8:11], v81 offset:16384
	ds_read_b128 v[12:15], v81 offset:20480
	s_waitcnt lgkmcnt(0)
	v_mfma_f32_32x32x16_bf16 v[48:63], v[0:3], v[8:11], 0
	v_add_u32_e32 v83, v119, v82
	v_add_u32_e32 v82, v120, v82
	ds_read_b128 v[84:87], v83
	ds_read_b128 v[102:105], v83 offset:4096
	ds_read_b128 v[106:109], v82 offset:16384
	ds_read_b128 v[110:113], v82 offset:20480
	s_mov_b32 m0, s85
	v_readfirstlane_b32 s64, v88
	v_readfirstlane_b32 s65, v89
	v_mfma_f32_32x32x16_bf16 v[32:47], v[0:3], v[12:15], 0
	v_lshl_or_b32 v128, s40, 7, v127
	s_andn2_b64 vcc, exec, s[76:77]
	v_or_b32_e32 v136, 32, v128
	v_mfma_f32_32x32x16_bf16 v[16:31], v[4:7], v[8:11], 0
	v_mfma_f32_32x32x16_bf16 v[0:15], v[4:7], v[12:15], 0
	s_waitcnt lgkmcnt(0)
	v_mfma_f32_32x32x16_bf16 v[48:63], v[84:87], v[106:109], v[48:63]
	v_mfma_f32_32x32x16_bf16 v[32:47], v[84:87], v[110:113], v[32:47]
	v_add_u32_e32 v87, v119, v114
	v_add_u32_e32 v85, v120, v114
	v_add_u32_e32 v84, v119, v118
	v_add_u32_e32 v86, v120, v118
	v_mfma_f32_32x32x16_bf16 v[16:31], v[102:105], v[106:109], v[16:31]
	v_mfma_f32_32x32x16_bf16 v[0:15], v[102:105], v[110:113], v[0:15]
	ds_read_b128 v[102:105], v87
	ds_read_b128 v[106:109], v87 offset:4096
	ds_read_b128 v[110:113], v85 offset:16384
	ds_read_b128 v[114:117], v85 offset:20480
	s_waitcnt lgkmcnt(0)
	v_mfma_f32_32x32x16_bf16 v[48:63], v[102:105], v[110:113], v[48:63]
	v_mfma_f32_32x32x16_bf16 v[32:47], v[102:105], v[114:117], v[32:47]
	v_mfma_f32_32x32x16_bf16 v[16:31], v[106:109], v[110:113], v[16:31]
	v_mfma_f32_32x32x16_bf16 v[0:15], v[106:109], v[114:117], v[0:15]
	ds_read_b128 v[102:105], v84
	ds_read_b128 v[106:109], v84 offset:4096
	ds_read_b128 v[110:113], v86 offset:16384
	ds_read_b128 v[114:117], v86 offset:20480
	s_waitcnt vmcnt(0)
	s_waitcnt vmcnt(0) lgkmcnt(0)
	s_barrier
; #define MFMA(a, b, c) __builtin_amdgcn_mfma_f32_32x32x16_bf16(a, b, c, 0, 0, 0)
; #define ISSUE(k0, bf) do { char* A_ = lw + (bf) * BUF; \
;     _Pragma("unroll") for (int i_ = 0; i_ < 4; ++i_) { glds16(al.ptr(lrow + 32 * i_, (k0) + cg), A_ + i_ * 4096); glds16(bl.ptr(lrow + 32 * i_, (k0) + cg), A_ + ABYTES + i_ * 4096); } \
;     if (HALO) { if (wid == 0) glds16(gh + (k0), A_ + 16384); } } while (0)
; template <bool HALO, class AL, class BL>
; __device__ __forceinline__ void gemm_core(f32x16 (&acc)[2][2], f32x16& hacc, const AL& al, const BL& bl, int K, char* lds,
;                                           const u16* halo0, const u16* halo1, int brow0, int brow1) {
;     ...
;   for (int kt = 0; kt < nk; ++kt) {
;     asm volatile("s_waitcnt vmcnt(0)" ::: "memory");
;     __syncthreads();
;     if (kt + 1 < nk) ISSUE((kt + 1) * 64, (kt + 1) & 1);
;     const char* T = lds + (kt & 1) * BUF;
; #pragma unroll
;     for (int kk = 0; kk < 4; ++kk) {
;       const int c = kk * 2 + hi;
;       bf16x8 a0 = *(const bf16x8*)(T + oa + ((c ^ sa) << 4));
;       bf16x8 a1 = *(const bf16x8*)(T + oa + 4096 + ((c ^ sa) << 4));
;       bf16x8 b0 = *(const bf16x8*)(T + ob0 + ((c ^ sb0) << 4));
;       bf16x8 b1 = *(const bf16x8*)(T + ob1 + ((c ^ sb1) << 4));
;       acc[0][0] = MFMA(a0, b0, acc[0][0]); acc[0][1] = MFMA(a0, b1, acc[0][1]);
;       acc[1][0] = MFMA(a1, b0, acc[1][0]); acc[1][1] = MFMA(a1, b1, acc[1][1]);
;       if (HALO) { bf16x8 ah = *(const bf16x8*)(T + oh + ((c ^ sh) << 4)); hacc = MFMA(ah, b0, hacc); }
;     }
	v_mfma_f32_32x32x16_bf16 v[48:63], v[102:105], v[110:113], v[48:63]
	v_mfma_f32_32x32x16_bf16 v[32:47], v[102:105], v[114:117], v[32:47]
	v_lshl_add_u64 v[102:103], v[64:65], 0, s[24:25]
	global_load_lds_dwordx4 v[102:103], off
	v_lshl_add_u64 v[102:103], v[66:67], 0, s[24:25]
	s_mov_b32 m0, s92
	s_nop 0
	global_load_lds_dwordx4 v[102:103], off
	v_lshl_add_u64 v[102:103], v[68:69], 0, s[24:25]
	s_mov_b32 m0, s70
	v_mfma_f32_32x32x16_bf16 v[16:31], v[106:109], v[110:113], v[16:31]
	global_load_lds_dwordx4 v[102:103], off
	v_lshl_add_u64 v[102:103], v[70:71], 0, s[24:25]
	s_mov_b32 m0, s71
	s_nop 0
	global_load_lds_dwordx4 v[102:103], off
	v_lshl_add_u64 v[102:103], v[72:73], 0, s[24:25]
	s_mov_b32 m0, s41
	v_mfma_f32_32x32x16_bf16 v[0:15], v[106:109], v[114:117], v[0:15]
	global_load_lds_dwordx4 v[102:103], off
	v_lshl_add_u64 v[102:103], v[74:75], 0, s[24:25]
	s_mov_b32 m0, s60
	s_nop 0
	global_load_lds_dwordx4 v[102:103], off
	v_lshl_add_u64 v[102:103], v[76:77], 0, s[24:25]
	s_mov_b32 m0, s61
	s_nop 0
	global_load_lds_dwordx4 v[102:103], off
	v_lshl_add_u64 v[102:103], v[78:79], 0, s[24:25]
	s_mov_b32 m0, s63
	s_nop 0
	global_load_lds_dwordx4 v[102:103], off
	ds_read_b128 v[102:105], v80 offset:32768
	ds_read_b128 v[106:109], v80 offset:36864
	ds_read_b128 v[110:113], v81 offset:49152
	ds_read_b128 v[114:117], v81 offset:53248
	s_waitcnt lgkmcnt(0)
	v_mfma_f32_32x32x16_bf16 v[48:63], v[102:105], v[110:113], v[48:63]
	s_mov_b32 m0, s69
	v_mfma_f32_32x32x16_bf16 v[32:47], v[102:105], v[114:117], v[32:47]
	v_mfma_f32_32x32x16_bf16 v[16:31], v[106:109], v[110:113], v[16:31]
	v_mfma_f32_32x32x16_bf16 v[0:15], v[106:109], v[114:117], v[0:15]
	ds_read_b128 v[102:105], v83 offset:32768
	ds_read_b128 v[106:109], v83 offset:36864
	ds_read_b128 v[110:113], v82 offset:49152
	ds_read_b128 v[114:117], v82 offset:53248
	s_waitcnt lgkmcnt(0)
	v_mfma_f32_32x32x16_bf16 v[48:63], v[102:105], v[110:113], v[48:63]
	v_mfma_f32_32x32x16_bf16 v[32:47], v[102:105], v[114:117], v[32:47]
	v_mfma_f32_32x32x16_bf16 v[16:31], v[106:109], v[110:113], v[16:31]
	v_mfma_f32_32x32x16_bf16 v[0:15], v[106:109], v[114:117], v[0:15]
	ds_read_b128 v[102:105], v87 offset:32768
	ds_read_b128 v[106:109], v87 offset:36864
	ds_read_b128 v[110:113], v85 offset:49152
	ds_read_b128 v[114:117], v85 offset:53248
	s_waitcnt lgkmcnt(0)
	v_mfma_f32_32x32x16_bf16 v[48:63], v[102:105], v[110:113], v[48:63]
	v_mfma_f32_32x32x16_bf16 v[32:47], v[102:105], v[114:117], v[32:47]
	v_mfma_f32_32x32x16_bf16 v[16:31], v[106:109], v[110:113], v[16:31]
	v_mfma_f32_32x32x16_bf16 v[0:15], v[106:109], v[114:117], v[0:15]
	ds_read_b128 v[102:105], v84 offset:32768
	ds_read_b128 v[106:109], v84 offset:36864
	ds_read_b128 v[110:113], v86 offset:49152
	ds_read_b128 v[114:117], v86 offset:53248
	s_waitcnt vmcnt(0)
	s_waitcnt vmcnt(0) lgkmcnt(0)
	s_barrier
	v_mfma_f32_32x32x16_bf16 v[48:63], v[102:105], v[110:113], v[48:63]
	v_mfma_f32_32x32x16_bf16 v[32:47], v[102:105], v[114:117], v[32:47]
	v_lshl_add_u64 v[102:103], v[64:65], 0, s[74:75]
	global_load_lds_dwordx4 v[102:103], off
	v_lshl_add_u64 v[102:103], v[66:67], 0, s[74:75]
	s_mov_b32 m0, s72
	s_nop 0
	global_load_lds_dwordx4 v[102:103], off
	v_lshl_add_u64 v[102:103], v[68:69], 0, s[74:75]
	s_mov_b32 m0, s73
	v_mfma_f32_32x32x16_bf16 v[16:31], v[106:109], v[110:113], v[16:31]
	global_load_lds_dwordx4 v[102:103], off
	v_lshl_add_u64 v[102:103], v[70:71], 0, s[74:75]
	s_mov_b32 m0, s80
	s_nop 0
	global_load_lds_dwordx4 v[102:103], off
	v_lshl_add_u64 v[102:103], v[72:73], 0, s[74:75]
	s_mov_b32 m0, s81
	v_mfma_f32_32x32x16_bf16 v[0:15], v[106:109], v[114:117], v[0:15]
	global_load_lds_dwordx4 v[102:103], off
	v_lshl_add_u64 v[102:103], v[74:75], 0, s[74:75]
	s_mov_b32 m0, s82
	s_nop 0
	global_load_lds_dwordx4 v[102:103], off
	v_lshl_add_u64 v[102:103], v[76:77], 0, s[74:75]
	s_mov_b32 m0, s83
	s_nop 0
	global_load_lds_dwordx4 v[102:103], off
	v_lshl_add_u64 v[102:103], v[78:79], 0, s[74:75]
	s_mov_b32 m0, s84
	s_nop 0
	global_load_lds_dwordx4 v[102:103], off
	ds_read_b128 v[102:105], v80
	ds_read_b128 v[106:109], v80 offset:4096
	ds_read_b128 v[110:113], v81 offset:16384
	ds_read_b128 v[114:117], v81 offset:20480
	s_waitcnt lgkmcnt(0)
	v_mfma_f32_32x32x16_bf16 v[48:63], v[102:105], v[110:113], v[48:63]
	s_mov_b32 m0, s85
	v_mfma_f32_32x32x16_bf16 v[32:47], v[102:105], v[114:117], v[32:47]
	v_mfma_f32_32x32x16_bf16 v[16:31], v[106:109], v[110:113], v[16:31]
	v_mfma_f32_32x32x16_bf16 v[0:15], v[106:109], v[114:117], v[0:15]
	ds_read_b128 v[102:105], v83
	ds_read_b128 v[106:109], v83 offset:4096
	ds_read_b128 v[110:113], v82 offset:16384
	ds_read_b128 v[114:117], v82 offset:20480
	s_waitcnt lgkmcnt(0)
	v_mfma_f32_32x32x16_bf16 v[48:63], v[102:105], v[110:113], v[48:63]
	v_mfma_f32_32x32x16_bf16 v[32:47], v[102:105], v[114:117], v[32:47]
	v_mfma_f32_32x32x16_bf16 v[16:31], v[106:109], v[110:113], v[16:31]
	v_mfma_f32_32x32x16_bf16 v[0:15], v[106:109], v[114:117], v[0:15]
	ds_read_b128 v[102:105], v87
	ds_read_b128 v[106:109], v87 offset:4096
	ds_read_b128 v[110:113], v85 offset:16384
	ds_read_b128 v[114:117], v85 offset:20480
	s_waitcnt lgkmcnt(0)
	v_mfma_f32_32x32x16_bf16 v[48:63], v[102:105], v[110:113], v[48:63]
	v_mfma_f32_32x32x16_bf16 v[32:47], v[102:105], v[114:117], v[32:47]
	v_mfma_f32_32x32x16_bf16 v[16:31], v[106:109], v[110:113], v[16:31]
	v_mfma_f32_32x32x16_bf16 v[0:15], v[106:109], v[114:117], v[0:15]
	ds_read_b128 v[102:105], v84
	ds_read_b128 v[106:109], v84 offset:4096
	ds_read_b128 v[110:113], v86 offset:16384
	ds_read_b128 v[114:117], v86 offset:20480
	s_waitcnt vmcnt(0)
	s_waitcnt vmcnt(0) lgkmcnt(0)
	s_barrier
; #define MFMA(a, b, c) __builtin_amdgcn_mfma_f32_32x32x16_bf16(a, b, c, 0, 0, 0)
; #define ISSUE(k0, bf) do { char* A_ = lw + (bf) * BUF; \
;     _Pragma("unroll") for (int i_ = 0; i_ < 4; ++i_) { glds16(al.ptr(lrow + 32 * i_, (k0) + cg), A_ + i_ * 4096); glds16(bl.ptr(lrow + 32 * i_, (k0) + cg), A_ + ABYTES + i_ * 4096); } \
;     if (HALO) { if (wid == 0) glds16(gh + (k0), A_ + 16384); } } while (0)
; template <bool HALO, class AL, class BL>
; __device__ __forceinline__ void gemm_core(f32x16 (&acc)[2][2], f32x16& hacc, const AL& al, const BL& bl, int K, char* lds,
;                                           const u16* halo0, const u16* halo1, int brow0, int brow1) {
;     ...
;   for (int kt = 0; kt < nk; ++kt) {
;     asm volatile("s_waitcnt vmcnt(0)" ::: "memory");
;     __syncthreads();
;     if (kt + 1 < nk) ISSUE((kt + 1) * 64, (kt + 1) & 1);
;     const char* T = lds + (kt & 1) * BUF;
; #pragma unroll
;     for (int kk = 0; kk < 4; ++kk) {
;       const int c = kk * 2 + hi;
;       bf16x8 a0 = *(const bf16x8*)(T + oa + ((c ^ sa) << 4));
;       bf16x8 a1 = *(const bf16x8*)(T + oa + 4096 + ((c ^ sa) << 4));
;       bf16x8 b0 = *(const bf16x8*)(T + ob0 + ((c ^ sb0) << 4));
;       bf16x8 b1 = *(const bf16x8*)(T + ob1 + ((c ^ sb1) << 4));
;       acc[0][0] = MFMA(a0, b0, acc[0][0]); acc[0][1] = MFMA(a0, b1, acc[0][1]);
;       acc[1][0] = MFMA(a1, b0, acc[1][0]); acc[1][1] = MFMA(a1, b1, acc[1][1]);
;       if (HALO) { bf16x8 ah = *(const bf16x8*)(T + oh + ((c ^ sh) << 4)); hacc = MFMA(ah, b0, hacc); }
;     }
	v_mfma_f32_32x32x16_bf16 v[48:63], v[102:105], v[110:113], v[48:63]
	v_mfma_f32_32x32x16_bf16 v[32:47], v[102:105], v[114:117], v[32:47]
	v_lshl_add_u64 v[102:103], v[64:65], 0, s[20:21]
	global_load_lds_dwordx4 v[102:103], off
	v_lshl_add_u64 v[102:103], v[66:67], 0, s[20:21]
	s_mov_b32 m0, s92
	s_nop 0
	global_load_lds_dwordx4 v[102:103], off
	v_lshl_add_u64 v[102:103], v[68:69], 0, s[20:21]
	s_mov_b32 m0, s70
	v_mfma_f32_32x32x16_bf16 v[16:31], v[106:109], v[110:113], v[16:31]
	global_load_lds_dwordx4 v[102:103], off
	v_lshl_add_u64 v[102:103], v[70:71], 0, s[20:21]
	s_mov_b32 m0, s71
	s_nop 0
	global_load_lds_dwordx4 v[102:103], off
	v_lshl_add_u64 v[102:103], v[72:73], 0, s[20:21]
	s_mov_b32 m0, s41
	v_mfma_f32_32x32x16_bf16 v[0:15], v[106:109], v[114:117], v[0:15]
	global_load_lds_dwordx4 v[102:103], off
	v_lshl_add_u64 v[102:103], v[74:75], 0, s[20:21]
	s_mov_b32 m0, s60
	s_nop 0
	global_load_lds_dwordx4 v[102:103], off
	v_lshl_add_u64 v[102:103], v[76:77], 0, s[20:21]
	s_mov_b32 m0, s61
	s_nop 0
	global_load_lds_dwordx4 v[102:103], off
	v_lshl_add_u64 v[102:103], v[78:79], 0, s[20:21]
	s_mov_b32 m0, s63
	s_nop 0
	global_load_lds_dwordx4 v[102:103], off
	ds_read_b128 v[102:105], v80 offset:32768
	ds_read_b128 v[106:109], v80 offset:36864
	ds_read_b128 v[110:113], v81 offset:49152
	ds_read_b128 v[114:117], v81 offset:53248
	s_waitcnt lgkmcnt(0)
	v_mfma_f32_32x32x16_bf16 v[48:63], v[102:105], v[110:113], v[48:63]
	s_mov_b32 m0, s69
	v_mfma_f32_32x32x16_bf16 v[32:47], v[102:105], v[114:117], v[32:47]
	v_mfma_f32_32x32x16_bf16 v[16:31], v[106:109], v[110:113], v[16:31]
	v_mfma_f32_32x32x16_bf16 v[0:15], v[106:109], v[114:117], v[0:15]
	ds_read_b128 v[102:105], v83 offset:32768
	ds_read_b128 v[106:109], v83 offset:36864
	ds_read_b128 v[110:113], v82 offset:49152
	ds_read_b128 v[114:117], v82 offset:53248
	s_waitcnt lgkmcnt(0)
	v_mfma_f32_32x32x16_bf16 v[48:63], v[102:105], v[110:113], v[48:63]
	v_mfma_f32_32x32x16_bf16 v[32:47], v[102:105], v[114:117], v[32:47]
	v_mfma_f32_32x32x16_bf16 v[16:31], v[106:109], v[110:113], v[16:31]
	v_mfma_f32_32x32x16_bf16 v[0:15], v[106:109], v[114:117], v[0:15]
	ds_read_b128 v[102:105], v87 offset:32768
	ds_read_b128 v[106:109], v87 offset:36864
	ds_read_b128 v[110:113], v85 offset:49152
	ds_read_b128 v[114:117], v85 offset:53248
	s_waitcnt lgkmcnt(0)
	v_mfma_f32_32x32x16_bf16 v[48:63], v[102:105], v[110:113], v[48:63]
	v_mfma_f32_32x32x16_bf16 v[32:47], v[102:105], v[114:117], v[32:47]
	v_mfma_f32_32x32x16_bf16 v[16:31], v[106:109], v[110:113], v[16:31]
	v_mfma_f32_32x32x16_bf16 v[0:15], v[106:109], v[114:117], v[0:15]
	ds_read_b128 v[102:105], v84 offset:32768
	ds_read_b128 v[106:109], v84 offset:36864
	ds_read_b128 v[110:113], v86 offset:49152
	ds_read_b128 v[114:117], v86 offset:53248
	s_waitcnt vmcnt(0)
	s_waitcnt vmcnt(0) lgkmcnt(0)
	s_barrier
	v_mfma_f32_32x32x16_bf16 v[48:63], v[102:105], v[110:113], v[48:63]
	v_mfma_f32_32x32x16_bf16 v[32:47], v[102:105], v[114:117], v[32:47]
	v_lshl_add_u64 v[102:103], v[64:65], 0, s[86:87]
	global_load_lds_dwordx4 v[102:103], off
	v_lshl_add_u64 v[102:103], v[66:67], 0, s[86:87]
	s_mov_b32 m0, s72
	s_nop 0
	global_load_lds_dwordx4 v[102:103], off
	v_lshl_add_u64 v[102:103], v[68:69], 0, s[86:87]
	s_mov_b32 m0, s73
	v_mfma_f32_32x32x16_bf16 v[16:31], v[106:109], v[110:113], v[16:31]
	global_load_lds_dwordx4 v[102:103], off
	v_lshl_add_u64 v[102:103], v[70:71], 0, s[86:87]
	s_mov_b32 m0, s80
	s_nop 0
	global_load_lds_dwordx4 v[102:103], off
	v_lshl_add_u64 v[102:103], v[72:73], 0, s[86:87]
	s_mov_b32 m0, s81
	v_mfma_f32_32x32x16_bf16 v[0:15], v[106:109], v[114:117], v[0:15]
	global_load_lds_dwordx4 v[102:103], off
	v_lshl_add_u64 v[102:103], v[74:75], 0, s[86:87]
	s_mov_b32 m0, s82
	s_nop 0
	global_load_lds_dwordx4 v[102:103], off
	v_lshl_add_u64 v[102:103], v[76:77], 0, s[86:87]
	s_mov_b32 m0, s83
	s_nop 0
	global_load_lds_dwordx4 v[102:103], off
	v_lshl_add_u64 v[102:103], v[78:79], 0, s[86:87]
	s_mov_b32 m0, s84
	s_nop 0
	global_load_lds_dwordx4 v[102:103], off
	ds_read_b128 v[102:105], v80
	ds_read_b128 v[106:109], v80 offset:4096
	ds_read_b128 v[110:113], v81 offset:16384
	ds_read_b128 v[114:117], v81 offset:20480
	s_waitcnt lgkmcnt(0)
	v_mfma_f32_32x32x16_bf16 v[48:63], v[102:105], v[110:113], v[48:63]
	s_mov_b32 m0, s85
	v_mfma_f32_32x32x16_bf16 v[32:47], v[102:105], v[114:117], v[32:47]
	v_mfma_f32_32x32x16_bf16 v[16:31], v[106:109], v[110:113], v[16:31]
	v_mfma_f32_32x32x16_bf16 v[0:15], v[106:109], v[114:117], v[0:15]
	ds_read_b128 v[102:105], v83
	ds_read_b128 v[106:109], v83 offset:4096
	ds_read_b128 v[110:113], v82 offset:16384
	ds_read_b128 v[114:117], v82 offset:20480
	s_waitcnt lgkmcnt(0)
	v_mfma_f32_32x32x16_bf16 v[48:63], v[102:105], v[110:113], v[48:63]
	v_mfma_f32_32x32x16_bf16 v[32:47], v[102:105], v[114:117], v[32:47]
	v_mfma_f32_32x32x16_bf16 v[16:31], v[106:109], v[110:113], v[16:31]
	v_mfma_f32_32x32x16_bf16 v[0:15], v[106:109], v[114:117], v[0:15]
	ds_read_b128 v[102:105], v87
	ds_read_b128 v[106:109], v87 offset:4096
	ds_read_b128 v[110:113], v85 offset:16384
	ds_read_b128 v[114:117], v85 offset:20480
	s_waitcnt lgkmcnt(0)
	v_mfma_f32_32x32x16_bf16 v[48:63], v[102:105], v[110:113], v[48:63]
	v_mfma_f32_32x32x16_bf16 v[32:47], v[102:105], v[114:117], v[32:47]
	v_mfma_f32_32x32x16_bf16 v[16:31], v[106:109], v[110:113], v[16:31]
	v_mfma_f32_32x32x16_bf16 v[0:15], v[106:109], v[114:117], v[0:15]
	ds_read_b128 v[102:105], v84
	ds_read_b128 v[106:109], v84 offset:4096
	ds_read_b128 v[110:113], v86 offset:16384
	ds_read_b128 v[114:117], v86 offset:20480
	s_waitcnt vmcnt(0)
	s_waitcnt vmcnt(0) lgkmcnt(0)
	s_barrier
; #define MFMA(a, b, c) __builtin_amdgcn_mfma_f32_32x32x16_bf16(a, b, c, 0, 0, 0)
; #define ISSUE(k0, bf) do { char* A_ = lw + (bf) * BUF; \
;     _Pragma("unroll") for (int i_ = 0; i_ < 4; ++i_) { glds16(al.ptr(lrow + 32 * i_, (k0) + cg), A_ + i_ * 4096); glds16(bl.ptr(lrow + 32 * i_, (k0) + cg), A_ + ABYTES + i_ * 4096); } \
;     if (HALO) { if (wid == 0) glds16(gh + (k0), A_ + 16384); } } while (0)
; template <bool HALO, class AL, class BL>
; __device__ __forceinline__ void gemm_core(f32x16 (&acc)[2][2], f32x16& hacc, const AL& al, const BL& bl, int K, char* lds,
;                                           const u16* halo0, const u16* halo1, int brow0, int brow1) {
;     ...
;   for (int kt = 0; kt < nk; ++kt) {
;     asm volatile("s_waitcnt vmcnt(0)" ::: "memory");
;     __syncthreads();
;     if (kt + 1 < nk) ISSUE((kt + 1) * 64, (kt + 1) & 1);
;     const char* T = lds + (kt & 1) * BUF;
; #pragma unroll
;     for (int kk = 0; kk < 4; ++kk) {
;       const int c = kk * 2 + hi;
;       bf16x8 a0 = *(const bf16x8*)(T + oa + ((c ^ sa) << 4));
;       bf16x8 a1 = *(const bf16x8*)(T + oa + 4096 + ((c ^ sa) << 4));
;       bf16x8 b0 = *(const bf16x8*)(T + ob0 + ((c ^ sb0) << 4));
;       bf16x8 b1 = *(const bf16x8*)(T + ob1 + ((c ^ sb1) << 4));
;       acc[0][0] = MFMA(a0, b0, acc[0][0]); acc[0][1] = MFMA(a0, b1, acc[0][1]);
;       acc[1][0] = MFMA(a1, b0, acc[1][0]); acc[1][1] = MFMA(a1, b1, acc[1][1]);
;       if (HALO) { bf16x8 ah = *(const bf16x8*)(T + oh + ((c ^ sh) << 4)); hacc = MFMA(ah, b0, hacc); }
;     }
	v_mfma_f32_32x32x16_bf16 v[48:63], v[102:105], v[110:113], v[48:63]
	v_mfma_f32_32x32x16_bf16 v[32:47], v[102:105], v[114:117], v[32:47]
	v_lshl_add_u64 v[102:103], v[64:65], 0, s[30:31]
	global_load_lds_dwordx4 v[102:103], off
	v_lshl_add_u64 v[102:103], v[66:67], 0, s[30:31]
	s_mov_b32 m0, s92
	s_nop 0
	global_load_lds_dwordx4 v[102:103], off
	v_lshl_add_u64 v[102:103], v[68:69], 0, s[30:31]
	s_mov_b32 m0, s70
	v_mfma_f32_32x32x16_bf16 v[16:31], v[106:109], v[110:113], v[16:31]
	global_load_lds_dwordx4 v[102:103], off
	v_lshl_add_u64 v[102:103], v[70:71], 0, s[30:31]
	s_mov_b32 m0, s71
	v_readfirstlane_b32 s70, v99
	global_load_lds_dwordx4 v[102:103], off
	v_lshl_add_u64 v[102:103], v[72:73], 0, s[30:31]
	s_mov_b32 m0, s41
	v_mfma_f32_32x32x16_bf16 v[0:15], v[106:109], v[114:117], v[0:15]
	global_load_lds_dwordx4 v[102:103], off
	v_lshl_add_u64 v[102:103], v[74:75], 0, s[30:31]
	s_mov_b32 m0, s60
	v_readfirstlane_b32 s71, v100
	global_load_lds_dwordx4 v[102:103], off
	v_lshl_add_u64 v[102:103], v[76:77], 0, s[30:31]
	s_mov_b32 m0, s61
	s_nop 0
	global_load_lds_dwordx4 v[102:103], off
	v_lshl_add_u64 v[102:103], v[78:79], 0, s[30:31]
	s_mov_b32 m0, s63
	s_nop 0
	global_load_lds_dwordx4 v[102:103], off
	ds_read_b128 v[102:105], v80 offset:32768
	ds_read_b128 v[106:109], v80 offset:36864
	ds_read_b128 v[110:113], v81 offset:49152
	ds_read_b128 v[114:117], v81 offset:53248
	s_waitcnt lgkmcnt(0)
	v_mfma_f32_32x32x16_bf16 v[48:63], v[102:105], v[110:113], v[48:63]
	s_mov_b32 m0, s69
	v_readfirstlane_b32 s69, v95
	v_mfma_f32_32x32x16_bf16 v[32:47], v[102:105], v[114:117], v[32:47]
	v_mfma_f32_32x32x16_bf16 v[16:31], v[106:109], v[110:113], v[16:31]
	v_mfma_f32_32x32x16_bf16 v[0:15], v[106:109], v[114:117], v[0:15]
	ds_read_b128 v[102:105], v83 offset:32768
	ds_read_b128 v[106:109], v83 offset:36864
	ds_read_b128 v[110:113], v82 offset:49152
	ds_read_b128 v[114:117], v82 offset:53248
	s_waitcnt lgkmcnt(0)
	v_mfma_f32_32x32x16_bf16 v[48:63], v[102:105], v[110:113], v[48:63]
	v_mfma_f32_32x32x16_bf16 v[32:47], v[102:105], v[114:117], v[32:47]
	v_mfma_f32_32x32x16_bf16 v[16:31], v[106:109], v[110:113], v[16:31]
	v_mfma_f32_32x32x16_bf16 v[0:15], v[106:109], v[114:117], v[0:15]
	ds_read_b128 v[102:105], v87 offset:32768
	ds_read_b128 v[106:109], v87 offset:36864
	ds_read_b128 v[110:113], v85 offset:49152
	ds_read_b128 v[114:117], v85 offset:53248
	s_waitcnt lgkmcnt(0)
	v_mfma_f32_32x32x16_bf16 v[48:63], v[102:105], v[110:113], v[48:63]
	v_mfma_f32_32x32x16_bf16 v[32:47], v[102:105], v[114:117], v[32:47]
	v_mfma_f32_32x32x16_bf16 v[16:31], v[106:109], v[110:113], v[16:31]
	v_mfma_f32_32x32x16_bf16 v[0:15], v[106:109], v[114:117], v[0:15]
	ds_read_b128 v[102:105], v84 offset:32768
	ds_read_b128 v[106:109], v84 offset:36864
	ds_read_b128 v[110:113], v86 offset:49152
	ds_read_b128 v[114:117], v86 offset:53248
	s_waitcnt vmcnt(0)
	s_waitcnt vmcnt(0) lgkmcnt(0)
	s_barrier
	v_mfma_f32_32x32x16_bf16 v[48:63], v[102:105], v[110:113], v[48:63]
	v_mfma_f32_32x32x16_bf16 v[32:47], v[102:105], v[114:117], v[32:47]
	v_lshl_add_u64 v[102:103], v[64:65], 0, s[4:5]
	global_load_lds_dwordx4 v[102:103], off
	v_lshl_add_u64 v[102:103], v[66:67], 0, s[4:5]
	s_mov_b32 m0, s72
	v_readfirstlane_b32 s72, v101
	global_load_lds_dwordx4 v[102:103], off
	v_lshl_add_u64 v[102:103], v[68:69], 0, s[4:5]
	s_mov_b32 m0, s73
	v_mfma_f32_32x32x16_bf16 v[16:31], v[106:109], v[110:113], v[16:31]
	global_load_lds_dwordx4 v[102:103], off
	v_lshl_add_u64 v[102:103], v[70:71], 0, s[4:5]
	s_mov_b32 m0, s80
	v_lshl_add_u64 v[100:101], v[72:73], 0, s[66:67]
	global_load_lds_dwordx4 v[102:103], off
	v_lshl_add_u64 v[102:103], v[72:73], 0, s[4:5]
	s_mov_b32 m0, s81
	v_mfma_f32_32x32x16_bf16 v[0:15], v[106:109], v[114:117], v[0:15]
	global_load_lds_dwordx4 v[102:103], off
	v_lshl_add_u64 v[102:103], v[74:75], 0, s[4:5]
	s_mov_b32 m0, s82
	v_readfirstlane_b32 s73, v92
	global_load_lds_dwordx4 v[102:103], off
	v_lshl_add_u64 v[102:103], v[76:77], 0, s[4:5]
	s_mov_b32 m0, s83
	v_readfirstlane_b32 s80, v93
	global_load_lds_dwordx4 v[102:103], off
	v_lshl_add_u64 v[102:103], v[78:79], 0, s[4:5]
	s_mov_b32 m0, s84
	v_readfirstlane_b32 s81, v94
	global_load_lds_dwordx4 v[102:103], off
	ds_read_b128 v[102:105], v80
	ds_read_b128 v[106:109], v80 offset:4096
	ds_read_b128 v[110:113], v81 offset:16384
	ds_read_b128 v[114:117], v81 offset:20480
	s_waitcnt lgkmcnt(0)
	v_mfma_f32_32x32x16_bf16 v[48:63], v[102:105], v[110:113], v[48:63]
	s_mov_b32 m0, s69
	v_readfirstlane_b32 s82, v96
	v_readfirstlane_b32 s83, v97
	v_readfirstlane_b32 s84, v98
	v_mfma_f32_32x32x16_bf16 v[32:47], v[102:105], v[114:117], v[32:47]
	v_mfma_f32_32x32x16_bf16 v[16:31], v[106:109], v[110:113], v[16:31]
	v_mfma_f32_32x32x16_bf16 v[0:15], v[106:109], v[114:117], v[0:15]
	ds_read_b128 v[102:105], v83
	ds_read_b128 v[106:109], v83 offset:4096
	ds_read_b128 v[110:113], v82 offset:16384
	ds_read_b128 v[114:117], v82 offset:20480
	s_waitcnt lgkmcnt(0)
	v_mfma_f32_32x32x16_bf16 v[48:63], v[102:105], v[110:113], v[48:63]
	v_mfma_f32_32x32x16_bf16 v[32:47], v[102:105], v[114:117], v[32:47]
	v_mfma_f32_32x32x16_bf16 v[16:31], v[106:109], v[110:113], v[16:31]
	v_mfma_f32_32x32x16_bf16 v[0:15], v[106:109], v[114:117], v[0:15]
	ds_read_b128 v[102:105], v87
	ds_read_b128 v[106:109], v87 offset:4096
	ds_read_b128 v[110:113], v85 offset:16384
	ds_read_b128 v[114:117], v85 offset:20480
	s_waitcnt lgkmcnt(0)
	v_mfma_f32_32x32x16_bf16 v[48:63], v[102:105], v[110:113], v[48:63]
	v_mfma_f32_32x32x16_bf16 v[32:47], v[102:105], v[114:117], v[32:47]
	v_mfma_f32_32x32x16_bf16 v[16:31], v[106:109], v[110:113], v[16:31]
	v_mfma_f32_32x32x16_bf16 v[0:15], v[106:109], v[114:117], v[0:15]
	ds_read_b128 v[102:105], v84
	ds_read_b128 v[106:109], v84 offset:4096
	ds_read_b128 v[110:113], v86 offset:16384
	ds_read_b128 v[114:117], v86 offset:20480
	s_waitcnt vmcnt(0)
	s_waitcnt vmcnt(0) lgkmcnt(0)
	s_barrier
; #define MFMA(a, b, c) __builtin_amdgcn_mfma_f32_32x32x16_bf16(a, b, c, 0, 0, 0)
; #define ISSUE(k0, bf) do { char* A_ = lw + (bf) * BUF; \
;     _Pragma("unroll") for (int i_ = 0; i_ < 4; ++i_) { glds16(al.ptr(lrow + 32 * i_, (k0) + cg), A_ + i_ * 4096); glds16(bl.ptr(lrow + 32 * i_, (k0) + cg), A_ + ABYTES + i_ * 4096); } \
;     if (HALO) { if (wid == 0) glds16(gh + (k0), A_ + 16384); } } while (0)
; template <bool HALO, class AL, class BL>
; __device__ __forceinline__ void gemm_core(f32x16 (&acc)[2][2], f32x16& hacc, const AL& al, const BL& bl, int K, char* lds,
;                                           const u16* halo0, const u16* halo1, int brow0, int brow1) {
;     ...
;   for (int kt = 0; kt < nk; ++kt) {
;     asm volatile("s_waitcnt vmcnt(0)" ::: "memory");
;     __syncthreads();
;     if (kt + 1 < nk) ISSUE((kt + 1) * 64, (kt + 1) & 1);
;     const char* T = lds + (kt & 1) * BUF;
; #pragma unroll
;     for (int kk = 0; kk < 4; ++kk) {
;       const int c = kk * 2 + hi;
;       bf16x8 a0 = *(const bf16x8*)(T + oa + ((c ^ sa) << 4));
;       bf16x8 a1 = *(const bf16x8*)(T + oa + 4096 + ((c ^ sa) << 4));
;       bf16x8 b0 = *(const bf16x8*)(T + ob0 + ((c ^ sb0) << 4));
;       bf16x8 b1 = *(const bf16x8*)(T + ob1 + ((c ^ sb1) << 4));
;       acc[0][0] = MFMA(a0, b0, acc[0][0]); acc[0][1] = MFMA(a0, b1, acc[0][1]);
;       acc[1][0] = MFMA(a1, b0, acc[1][0]); acc[1][1] = MFMA(a1, b1, acc[1][1]);
;       if (HALO) { bf16x8 ah = *(const bf16x8*)(T + oh + ((c ^ sh) << 4)); hacc = MFMA(ah, b0, hacc); }
;     }
	v_mfma_f32_32x32x16_bf16 v[48:63], v[102:105], v[110:113], v[48:63]
	v_mfma_f32_32x32x16_bf16 v[32:47], v[102:105], v[114:117], v[32:47]
	v_lshl_add_u64 v[102:103], v[64:65], 0, s[66:67]
	global_load_lds_dwordx4 v[102:103], off
	v_lshl_add_u64 v[102:103], v[66:67], 0, s[66:67]
	s_mov_b32 m0, s70
	s_nop 0
	global_load_lds_dwordx4 v[102:103], off
	v_lshl_add_u64 v[102:103], v[68:69], 0, s[66:67]
	s_mov_b32 m0, s71
	v_mfma_f32_32x32x16_bf16 v[16:31], v[106:109], v[110:113], v[16:31]
	global_load_lds_dwordx4 v[102:103], off
	v_lshl_add_u64 v[102:103], v[70:71], 0, s[66:67]
	s_mov_b32 m0, s72
	s_nop 0
	global_load_lds_dwordx4 v[102:103], off
	s_mov_b32 m0, s41
	v_mfma_f32_32x32x16_bf16 v[0:15], v[106:109], v[114:117], v[0:15]
	global_load_lds_dwordx4 v[100:101], off
	v_lshl_add_u64 v[100:101], v[74:75], 0, s[66:67]
	s_mov_b32 m0, s60
	s_nop 0
	global_load_lds_dwordx4 v[100:101], off
	v_lshl_add_u64 v[100:101], v[76:77], 0, s[66:67]
	s_mov_b32 m0, s61
	v_readfirstlane_b32 s61, v91
	global_load_lds_dwordx4 v[100:101], off
	v_lshl_add_u64 v[100:101], v[78:79], 0, s[66:67]
	s_mov_b32 m0, s63
	v_readfirstlane_b32 s63, v90
	global_load_lds_dwordx4 v[100:101], off
	ds_read_b128 v[100:103], v80 offset:32768
	ds_read_b128 v[104:107], v80 offset:36864
	ds_read_b128 v[108:111], v81 offset:49152
	ds_read_b128 v[112:115], v81 offset:53248
	s_waitcnt lgkmcnt(0)
	v_mfma_f32_32x32x16_bf16 v[48:63], v[100:103], v[108:111], v[48:63]
	s_mov_b32 m0, s61
	v_lshl_add_u64 v[90:91], v[68:69], 0, s[26:27]
	v_mfma_f32_32x32x16_bf16 v[32:47], v[100:103], v[112:115], v[32:47]
	v_mfma_f32_32x32x16_bf16 v[16:31], v[104:107], v[108:111], v[16:31]
	v_mfma_f32_32x32x16_bf16 v[0:15], v[104:107], v[112:115], v[0:15]
	ds_read_b128 v[100:103], v83 offset:32768
	ds_read_b128 v[104:107], v83 offset:36864
	ds_read_b128 v[108:111], v82 offset:49152
	ds_read_b128 v[112:115], v82 offset:53248
	s_waitcnt lgkmcnt(0)
	v_mfma_f32_32x32x16_bf16 v[48:63], v[100:103], v[108:111], v[48:63]
	v_mfma_f32_32x32x16_bf16 v[32:47], v[100:103], v[112:115], v[32:47]
	v_mfma_f32_32x32x16_bf16 v[16:31], v[104:107], v[108:111], v[16:31]
	v_mfma_f32_32x32x16_bf16 v[0:15], v[104:107], v[112:115], v[0:15]
	ds_read_b128 v[100:103], v87 offset:32768
	ds_read_b128 v[104:107], v87 offset:36864
	ds_read_b128 v[108:111], v85 offset:49152
	ds_read_b128 v[112:115], v85 offset:53248
	s_waitcnt lgkmcnt(0)
	v_mfma_f32_32x32x16_bf16 v[48:63], v[100:103], v[108:111], v[48:63]
	v_mfma_f32_32x32x16_bf16 v[32:47], v[100:103], v[112:115], v[32:47]
	v_mfma_f32_32x32x16_bf16 v[16:31], v[104:107], v[108:111], v[16:31]
	v_mfma_f32_32x32x16_bf16 v[0:15], v[104:107], v[112:115], v[0:15]
	ds_read_b128 v[100:103], v84 offset:32768
	ds_read_b128 v[104:107], v84 offset:36864
	ds_read_b128 v[108:111], v86 offset:49152
	ds_read_b128 v[112:115], v86 offset:53248
	s_waitcnt vmcnt(0)
	s_waitcnt vmcnt(0) lgkmcnt(0)
	s_barrier
	v_mfma_f32_32x32x16_bf16 v[48:63], v[100:103], v[108:111], v[48:63]
	v_mfma_f32_32x32x16_bf16 v[32:47], v[100:103], v[112:115], v[32:47]
	v_lshl_add_u64 v[100:101], v[64:65], 0, s[26:27]
	global_load_lds_dwordx4 v[100:101], off
	v_lshl_add_u64 v[100:101], v[66:67], 0, s[26:27]
	s_mov_b32 m0, s63
	s_nop 0
	global_load_lds_dwordx4 v[100:101], off
	s_mov_b32 m0, s73
	v_mfma_f32_32x32x16_bf16 v[16:31], v[104:107], v[108:111], v[16:31]
	global_load_lds_dwordx4 v[90:91], off
	v_lshl_add_u64 v[90:91], v[70:71], 0, s[26:27]
	s_mov_b32 m0, s80
	s_nop 0
	global_load_lds_dwordx4 v[90:91], off
	v_lshl_add_u64 v[90:91], v[72:73], 0, s[26:27]
	s_mov_b32 m0, s81
	v_mfma_f32_32x32x16_bf16 v[0:15], v[104:107], v[112:115], v[0:15]
	global_load_lds_dwordx4 v[90:91], off
	v_lshl_add_u64 v[90:91], v[74:75], 0, s[26:27]
	s_mov_b32 m0, s82
	s_nop 0
	global_load_lds_dwordx4 v[90:91], off
	v_lshl_add_u64 v[90:91], v[76:77], 0, s[26:27]
	s_mov_b32 m0, s83
	s_nop 0
	global_load_lds_dwordx4 v[90:91], off
	v_lshl_add_u64 v[90:91], v[78:79], 0, s[26:27]
	s_mov_b32 m0, s84
	s_nop 0
	global_load_lds_dwordx4 v[90:91], off
	ds_read_b128 v[90:93], v80
	ds_read_b128 v[94:97], v80 offset:4096
	ds_read_b128 v[98:101], v81 offset:16384
	ds_read_b128 v[102:105], v81 offset:20480
	s_waitcnt lgkmcnt(0)
	v_mfma_f32_32x32x16_bf16 v[48:63], v[90:93], v[98:101], v[48:63]
	s_mov_b32 m0, s69
	v_mfma_f32_32x32x16_bf16 v[32:47], v[90:93], v[102:105], v[32:47]
	v_mfma_f32_32x32x16_bf16 v[16:31], v[94:97], v[98:101], v[16:31]
	v_mfma_f32_32x32x16_bf16 v[0:15], v[94:97], v[102:105], v[0:15]
	ds_read_b128 v[90:93], v83
	ds_read_b128 v[94:97], v83 offset:4096
	ds_read_b128 v[98:101], v82 offset:16384
	ds_read_b128 v[102:105], v82 offset:20480
	s_waitcnt lgkmcnt(0)
	v_mfma_f32_32x32x16_bf16 v[48:63], v[90:93], v[98:101], v[48:63]
	v_mfma_f32_32x32x16_bf16 v[32:47], v[90:93], v[102:105], v[32:47]
	v_mfma_f32_32x32x16_bf16 v[16:31], v[94:97], v[98:101], v[16:31]
	v_mfma_f32_32x32x16_bf16 v[0:15], v[94:97], v[102:105], v[0:15]
	ds_read_b128 v[90:93], v87
	ds_read_b128 v[94:97], v87 offset:4096
	ds_read_b128 v[98:101], v85 offset:16384
	ds_read_b128 v[102:105], v85 offset:20480
	s_waitcnt lgkmcnt(0)
	v_mfma_f32_32x32x16_bf16 v[48:63], v[90:93], v[98:101], v[48:63]
	v_mfma_f32_32x32x16_bf16 v[32:47], v[90:93], v[102:105], v[32:47]
	v_mfma_f32_32x32x16_bf16 v[16:31], v[94:97], v[98:101], v[16:31]
	v_mfma_f32_32x32x16_bf16 v[0:15], v[94:97], v[102:105], v[0:15]
	ds_read_b128 v[90:93], v84
	ds_read_b128 v[94:97], v84 offset:4096
	ds_read_b128 v[98:101], v86 offset:16384
	ds_read_b128 v[102:105], v86 offset:20480
	s_waitcnt vmcnt(0)
	s_waitcnt vmcnt(0) lgkmcnt(0)
	s_barrier
; #define MFMA(a, b, c) __builtin_amdgcn_mfma_f32_32x32x16_bf16(a, b, c, 0, 0, 0)
; #define ISSUE(k0, bf) do { char* A_ = lw + (bf) * BUF; \
;     _Pragma("unroll") for (int i_ = 0; i_ < 4; ++i_) { glds16(al.ptr(lrow + 32 * i_, (k0) + cg), A_ + i_ * 4096); glds16(bl.ptr(lrow + 32 * i_, (k0) + cg), A_ + ABYTES + i_ * 4096); } \
;     if (HALO) { if (wid == 0) glds16(gh + (k0), A_ + 16384); } } while (0)
; template <bool HALO, class AL, class BL>
; __device__ __forceinline__ void gemm_core(f32x16 (&acc)[2][2], f32x16& hacc, const AL& al, const BL& bl, int K, char* lds,
;                                           const u16* halo0, const u16* halo1, int brow0, int brow1) {
;     ...
;   for (int kt = 0; kt < nk; ++kt) {
;     asm volatile("s_waitcnt vmcnt(0)" ::: "memory");
;     __syncthreads();
;     if (kt + 1 < nk) ISSUE((kt + 1) * 64, (kt + 1) & 1);
;     const char* T = lds + (kt & 1) * BUF;
; #pragma unroll
;     for (int kk = 0; kk < 4; ++kk) {
;       const int c = kk * 2 + hi;
;       bf16x8 a0 = *(const bf16x8*)(T + oa + ((c ^ sa) << 4));
;       bf16x8 a1 = *(const bf16x8*)(T + oa + 4096 + ((c ^ sa) << 4));
;       bf16x8 b0 = *(const bf16x8*)(T + ob0 + ((c ^ sb0) << 4));
;       bf16x8 b1 = *(const bf16x8*)(T + ob1 + ((c ^ sb1) << 4));
;       acc[0][0] = MFMA(a0, b0, acc[0][0]); acc[0][1] = MFMA(a0, b1, acc[0][1]);
;       acc[1][0] = MFMA(a1, b0, acc[1][0]); acc[1][1] = MFMA(a1, b1, acc[1][1]);
;       if (HALO) { bf16x8 ah = *(const bf16x8*)(T + oh + ((c ^ sh) << 4)); hacc = MFMA(ah, b0, hacc); }
;     }
	v_mfma_f32_32x32x16_bf16 v[48:63], v[90:93], v[98:101], v[48:63]
	v_mfma_f32_32x32x16_bf16 v[32:47], v[90:93], v[102:105], v[32:47]
	v_lshl_add_u64 v[90:91], v[64:65], 0, s[88:89]
	global_load_lds_dwordx4 v[90:91], off
	v_lshl_add_u64 v[90:91], v[66:67], 0, s[88:89]
	s_mov_b32 m0, s70
	s_nop 0
	global_load_lds_dwordx4 v[90:91], off
	v_lshl_add_u64 v[90:91], v[68:69], 0, s[88:89]
	s_mov_b32 m0, s71
	v_mfma_f32_32x32x16_bf16 v[16:31], v[94:97], v[98:101], v[16:31]
	global_load_lds_dwordx4 v[90:91], off
	v_lshl_add_u64 v[90:91], v[70:71], 0, s[88:89]
	s_mov_b32 m0, s72
	s_nop 0
	global_load_lds_dwordx4 v[90:91], off
	v_lshl_add_u64 v[90:91], v[72:73], 0, s[88:89]
	s_mov_b32 m0, s41
	v_mfma_f32_32x32x16_bf16 v[0:15], v[94:97], v[102:105], v[0:15]
	global_load_lds_dwordx4 v[90:91], off
	v_lshl_add_u64 v[90:91], v[74:75], 0, s[88:89]
	s_mov_b32 m0, s60
	s_nop 0
	global_load_lds_dwordx4 v[90:91], off
	v_lshl_add_u64 v[90:91], v[76:77], 0, s[88:89]
	s_mov_b32 m0, s64
	s_nop 0
	global_load_lds_dwordx4 v[90:91], off
	v_lshl_add_u64 v[90:91], v[78:79], 0, s[88:89]
	s_mov_b32 m0, s65
	s_nop 0
	global_load_lds_dwordx4 v[90:91], off
	ds_read_b128 v[88:91], v80 offset:32768
	ds_read_b128 v[92:95], v80 offset:36864
	ds_read_b128 v[96:99], v81 offset:49152
	ds_read_b128 v[100:103], v81 offset:53248
	s_waitcnt lgkmcnt(0)
	v_mfma_f32_32x32x16_bf16 v[48:63], v[88:91], v[96:99], v[48:63]
	s_mov_b32 m0, s61
	v_mfma_f32_32x32x16_bf16 v[32:47], v[88:91], v[100:103], v[32:47]
	v_mfma_f32_32x32x16_bf16 v[16:31], v[92:95], v[96:99], v[16:31]
	v_mfma_f32_32x32x16_bf16 v[0:15], v[92:95], v[100:103], v[0:15]
	ds_read_b128 v[88:91], v83 offset:32768
	ds_read_b128 v[92:95], v83 offset:36864
	ds_read_b128 v[96:99], v82 offset:49152
	ds_read_b128 v[100:103], v82 offset:53248
	s_waitcnt lgkmcnt(0)
	v_mfma_f32_32x32x16_bf16 v[48:63], v[88:91], v[96:99], v[48:63]
	v_mfma_f32_32x32x16_bf16 v[32:47], v[88:91], v[100:103], v[32:47]
	v_mfma_f32_32x32x16_bf16 v[16:31], v[92:95], v[96:99], v[16:31]
	v_mfma_f32_32x32x16_bf16 v[0:15], v[92:95], v[100:103], v[0:15]
	ds_read_b128 v[88:91], v87 offset:32768
	ds_read_b128 v[92:95], v87 offset:36864
	ds_read_b128 v[96:99], v85 offset:49152
	ds_read_b128 v[100:103], v85 offset:53248
	s_waitcnt lgkmcnt(0)
	v_mfma_f32_32x32x16_bf16 v[48:63], v[88:91], v[96:99], v[48:63]
	v_mfma_f32_32x32x16_bf16 v[32:47], v[88:91], v[100:103], v[32:47]
	v_mfma_f32_32x32x16_bf16 v[16:31], v[92:95], v[96:99], v[16:31]
	v_mfma_f32_32x32x16_bf16 v[0:15], v[92:95], v[100:103], v[0:15]
	ds_read_b128 v[88:91], v84 offset:32768
	ds_read_b128 v[92:95], v84 offset:36864
	ds_read_b128 v[96:99], v86 offset:49152
	ds_read_b128 v[100:103], v86 offset:53248
	s_waitcnt vmcnt(0)
	s_waitcnt vmcnt(0) lgkmcnt(0)
	s_barrier
	v_mfma_f32_32x32x16_bf16 v[48:63], v[88:91], v[96:99], v[48:63]
	v_mfma_f32_32x32x16_bf16 v[32:47], v[88:91], v[100:103], v[32:47]
	v_lshl_add_u64 v[88:89], v[64:65], 0, s[22:23]
	global_load_lds_dwordx4 v[88:89], off
	v_lshl_add_u64 v[88:89], v[66:67], 0, s[22:23]
	s_mov_b32 m0, s63
	s_nop 0
	global_load_lds_dwordx4 v[88:89], off
	v_lshl_add_u64 v[88:89], v[68:69], 0, s[22:23]
	s_mov_b32 m0, s73
	v_mfma_f32_32x32x16_bf16 v[16:31], v[92:95], v[96:99], v[16:31]
	global_load_lds_dwordx4 v[88:89], off
	v_lshl_add_u64 v[88:89], v[70:71], 0, s[22:23]
	s_mov_b32 m0, s80
	s_nop 0
	global_load_lds_dwordx4 v[88:89], off
	v_lshl_add_u64 v[88:89], v[72:73], 0, s[22:23]
	s_mov_b32 m0, s81
	v_mfma_f32_32x32x16_bf16 v[0:15], v[92:95], v[100:103], v[0:15]
	global_load_lds_dwordx4 v[88:89], off
	v_lshl_add_u64 v[88:89], v[74:75], 0, s[22:23]
	s_mov_b32 m0, s82
	s_nop 0
	global_load_lds_dwordx4 v[88:89], off
	v_lshl_add_u64 v[88:89], v[76:77], 0, s[22:23]
	s_mov_b32 m0, s83
	s_nop 0
	global_load_lds_dwordx4 v[88:89], off
	v_lshl_add_u64 v[88:89], v[78:79], 0, s[22:23]
	s_mov_b32 m0, s84
	s_nop 0
	global_load_lds_dwordx4 v[88:89], off
	ds_read_b128 v[88:91], v80
	ds_read_b128 v[92:95], v80 offset:4096
	ds_read_b128 v[96:99], v81 offset:16384
	ds_read_b128 v[100:103], v81 offset:20480
	s_waitcnt lgkmcnt(0)
	v_mfma_f32_32x32x16_bf16 v[48:63], v[88:91], v[96:99], v[48:63]
	s_mov_b32 m0, s69
	v_mfma_f32_32x32x16_bf16 v[32:47], v[88:91], v[100:103], v[32:47]
	v_mfma_f32_32x32x16_bf16 v[16:31], v[92:95], v[96:99], v[16:31]
	v_mfma_f32_32x32x16_bf16 v[0:15], v[92:95], v[100:103], v[0:15]
	ds_read_b128 v[88:91], v83
	ds_read_b128 v[92:95], v83 offset:4096
	ds_read_b128 v[96:99], v82 offset:16384
	ds_read_b128 v[100:103], v82 offset:20480
	s_waitcnt lgkmcnt(0)
	v_mfma_f32_32x32x16_bf16 v[48:63], v[88:91], v[96:99], v[48:63]
	v_mfma_f32_32x32x16_bf16 v[32:47], v[88:91], v[100:103], v[32:47]
	v_mfma_f32_32x32x16_bf16 v[16:31], v[92:95], v[96:99], v[16:31]
	v_mfma_f32_32x32x16_bf16 v[0:15], v[92:95], v[100:103], v[0:15]
	ds_read_b128 v[88:91], v87
	ds_read_b128 v[92:95], v87 offset:4096
	ds_read_b128 v[96:99], v85 offset:16384
	ds_read_b128 v[100:103], v85 offset:20480
	s_waitcnt lgkmcnt(0)
	v_mfma_f32_32x32x16_bf16 v[48:63], v[88:91], v[96:99], v[48:63]
	v_mfma_f32_32x32x16_bf16 v[32:47], v[88:91], v[100:103], v[32:47]
	v_mfma_f32_32x32x16_bf16 v[16:31], v[92:95], v[96:99], v[16:31]
	v_mfma_f32_32x32x16_bf16 v[0:15], v[92:95], v[100:103], v[0:15]
	ds_read_b128 v[88:91], v84
	ds_read_b128 v[92:95], v84 offset:4096
	ds_read_b128 v[96:99], v86 offset:16384
	ds_read_b128 v[100:103], v86 offset:20480
	s_waitcnt vmcnt(0)
	s_waitcnt vmcnt(0) lgkmcnt(0)
	s_barrier
; #define MFMA(a, b, c) __builtin_amdgcn_mfma_f32_32x32x16_bf16(a, b, c, 0, 0, 0)
; #define ISSUE(k0, bf) do { char* A_ = lw + (bf) * BUF; \
;     _Pragma("unroll") for (int i_ = 0; i_ < 4; ++i_) { glds16(al.ptr(lrow + 32 * i_, (k0) + cg), A_ + i_ * 4096); glds16(bl.ptr(lrow + 32 * i_, (k0) + cg), A_ + ABYTES + i_ * 4096); } \
;     if (HALO) { if (wid == 0) glds16(gh + (k0), A_ + 16384); } } while (0)
; template <bool HALO, class AL, class BL>
; __device__ __forceinline__ void gemm_core(f32x16 (&acc)[2][2], f32x16& hacc, const AL& al, const BL& bl, int K, char* lds,
;                                           const u16* halo0, const u16* halo1, int brow0, int brow1) {
;     ...
;   for (int kt = 0; kt < nk; ++kt) {
;     asm volatile("s_waitcnt vmcnt(0)" ::: "memory");
;     __syncthreads();
;     if (kt + 1 < nk) ISSUE((kt + 1) * 64, (kt + 1) & 1);
;     const char* T = lds + (kt & 1) * BUF;
; #pragma unroll
;     for (int kk = 0; kk < 4; ++kk) {
;       const int c = kk * 2 + hi;
;       bf16x8 a0 = *(const bf16x8*)(T + oa + ((c ^ sa) << 4));
;       bf16x8 a1 = *(const bf16x8*)(T + oa + 4096 + ((c ^ sa) << 4));
;       bf16x8 b0 = *(const bf16x8*)(T + ob0 + ((c ^ sb0) << 4));
;       bf16x8 b1 = *(const bf16x8*)(T + ob1 + ((c ^ sb1) << 4));
;       acc[0][0] = MFMA(a0, b0, acc[0][0]); acc[0][1] = MFMA(a0, b1, acc[0][1]);
;       acc[1][0] = MFMA(a1, b0, acc[1][0]); acc[1][1] = MFMA(a1, b1, acc[1][1]);
;       if (HALO) { bf16x8 ah = *(const bf16x8*)(T + oh + ((c ^ sh) << 4)); hacc = MFMA(ah, b0, hacc); }
;     }
	v_mfma_f32_32x32x16_bf16 v[48:63], v[88:91], v[96:99], v[48:63]
	v_mfma_f32_32x32x16_bf16 v[32:47], v[88:91], v[100:103], v[32:47]
	v_lshl_add_u64 v[88:89], v[64:65], 0, s[90:91]
	global_load_lds_dwordx4 v[88:89], off
	v_lshl_add_u64 v[88:89], v[66:67], 0, s[90:91]
	s_mov_b32 m0, s70
	s_nop 0
	global_load_lds_dwordx4 v[88:89], off
	v_lshl_add_u64 v[88:89], v[68:69], 0, s[90:91]
	s_mov_b32 m0, s71
	v_mfma_f32_32x32x16_bf16 v[16:31], v[92:95], v[96:99], v[16:31]
	global_load_lds_dwordx4 v[88:89], off
	v_lshl_add_u64 v[88:89], v[70:71], 0, s[90:91]
	s_mov_b32 m0, s72
	s_nop 0
	global_load_lds_dwordx4 v[88:89], off
	v_lshl_add_u64 v[88:89], v[72:73], 0, s[90:91]
	s_mov_b32 m0, s41
	v_mfma_f32_32x32x16_bf16 v[0:15], v[92:95], v[100:103], v[0:15]
	global_load_lds_dwordx4 v[88:89], off
	v_lshl_add_u64 v[88:89], v[74:75], 0, s[90:91]
	s_mov_b32 m0, s60
	s_nop 0
	global_load_lds_dwordx4 v[88:89], off
	v_lshl_add_u64 v[88:89], v[76:77], 0, s[90:91]
	s_mov_b32 m0, s64
	s_nop 0
	global_load_lds_dwordx4 v[88:89], off
	v_lshl_add_u64 v[88:89], v[78:79], 0, s[90:91]
	s_mov_b32 m0, s65
	s_nop 0
	global_load_lds_dwordx4 v[88:89], off
	ds_read_b128 v[88:91], v80 offset:32768
	ds_read_b128 v[92:95], v80 offset:36864
	ds_read_b128 v[96:99], v81 offset:49152
	ds_read_b128 v[100:103], v81 offset:53248
	s_waitcnt lgkmcnt(0)
	v_mfma_f32_32x32x16_bf16 v[48:63], v[88:91], v[96:99], v[48:63]
	s_mov_b32 m0, s61
	v_mfma_f32_32x32x16_bf16 v[32:47], v[88:91], v[100:103], v[32:47]
	v_mfma_f32_32x32x16_bf16 v[16:31], v[92:95], v[96:99], v[16:31]
	v_mfma_f32_32x32x16_bf16 v[0:15], v[92:95], v[100:103], v[0:15]
	ds_read_b128 v[88:91], v83 offset:32768
	ds_read_b128 v[92:95], v83 offset:36864
	ds_read_b128 v[96:99], v82 offset:49152
	ds_read_b128 v[100:103], v82 offset:53248
	s_waitcnt lgkmcnt(0)
	v_mfma_f32_32x32x16_bf16 v[48:63], v[88:91], v[96:99], v[48:63]
	v_mfma_f32_32x32x16_bf16 v[32:47], v[88:91], v[100:103], v[32:47]
	v_mfma_f32_32x32x16_bf16 v[16:31], v[92:95], v[96:99], v[16:31]
	v_mfma_f32_32x32x16_bf16 v[0:15], v[92:95], v[100:103], v[0:15]
	ds_read_b128 v[88:91], v87 offset:32768
	ds_read_b128 v[92:95], v87 offset:36864
	ds_read_b128 v[96:99], v85 offset:49152
	ds_read_b128 v[100:103], v85 offset:53248
	s_waitcnt lgkmcnt(0)
	v_mfma_f32_32x32x16_bf16 v[48:63], v[88:91], v[96:99], v[48:63]
	v_mfma_f32_32x32x16_bf16 v[32:47], v[88:91], v[100:103], v[32:47]
	v_mfma_f32_32x32x16_bf16 v[16:31], v[92:95], v[96:99], v[16:31]
	v_mfma_f32_32x32x16_bf16 v[0:15], v[92:95], v[100:103], v[0:15]
	ds_read_b128 v[88:91], v84 offset:32768
	ds_read_b128 v[92:95], v84 offset:36864
	ds_read_b128 v[96:99], v86 offset:49152
	ds_read_b128 v[100:103], v86 offset:53248
	s_waitcnt vmcnt(0)
	s_waitcnt vmcnt(0) lgkmcnt(0)
	s_barrier
	v_mfma_f32_32x32x16_bf16 v[48:63], v[88:91], v[96:99], v[48:63]
	v_mfma_f32_32x32x16_bf16 v[32:47], v[88:91], v[100:103], v[32:47]
	v_lshl_add_u64 v[88:89], v[64:65], 0, s[0:1]
	global_load_lds_dwordx4 v[88:89], off
	v_lshl_add_u64 v[88:89], v[66:67], 0, s[0:1]
	s_mov_b32 m0, s63
	s_nop 0
	global_load_lds_dwordx4 v[88:89], off
	v_lshl_add_u64 v[88:89], v[68:69], 0, s[0:1]
	s_mov_b32 m0, s73
	v_mfma_f32_32x32x16_bf16 v[16:31], v[92:95], v[96:99], v[16:31]
	global_load_lds_dwordx4 v[88:89], off
	v_lshl_add_u64 v[88:89], v[70:71], 0, s[0:1]
	s_mov_b32 m0, s80
	s_nop 0
	global_load_lds_dwordx4 v[88:89], off
	v_lshl_add_u64 v[88:89], v[72:73], 0, s[0:1]
	s_mov_b32 m0, s81
	v_mfma_f32_32x32x16_bf16 v[0:15], v[92:95], v[100:103], v[0:15]
	global_load_lds_dwordx4 v[88:89], off
	v_lshl_add_u64 v[88:89], v[74:75], 0, s[0:1]
	s_mov_b32 m0, s82
	s_nop 0
	global_load_lds_dwordx4 v[88:89], off
	v_lshl_add_u64 v[88:89], v[76:77], 0, s[0:1]
	s_mov_b32 m0, s83
	s_nop 0
	global_load_lds_dwordx4 v[88:89], off
	v_lshl_add_u64 v[88:89], v[78:79], 0, s[0:1]
	s_mov_b32 m0, s84
	s_nop 0
	global_load_lds_dwordx4 v[88:89], off
	ds_read_b128 v[88:91], v80
	ds_read_b128 v[92:95], v80 offset:4096
	ds_read_b128 v[96:99], v81 offset:16384
	ds_read_b128 v[100:103], v81 offset:20480
	s_waitcnt lgkmcnt(0)
	v_mfma_f32_32x32x16_bf16 v[48:63], v[88:91], v[96:99], v[48:63]
	s_mov_b32 m0, s69
	v_mfma_f32_32x32x16_bf16 v[32:47], v[88:91], v[100:103], v[32:47]
	v_mfma_f32_32x32x16_bf16 v[16:31], v[92:95], v[96:99], v[16:31]
	v_mfma_f32_32x32x16_bf16 v[0:15], v[92:95], v[100:103], v[0:15]
	ds_read_b128 v[88:91], v83
	ds_read_b128 v[92:95], v83 offset:4096
	ds_read_b128 v[96:99], v82 offset:16384
	ds_read_b128 v[100:103], v82 offset:20480
	s_waitcnt lgkmcnt(0)
	v_mfma_f32_32x32x16_bf16 v[48:63], v[88:91], v[96:99], v[48:63]
	v_mfma_f32_32x32x16_bf16 v[32:47], v[88:91], v[100:103], v[32:47]
	v_mfma_f32_32x32x16_bf16 v[16:31], v[92:95], v[96:99], v[16:31]
	v_mfma_f32_32x32x16_bf16 v[0:15], v[92:95], v[100:103], v[0:15]
	ds_read_b128 v[88:91], v87
	ds_read_b128 v[92:95], v87 offset:4096
	ds_read_b128 v[96:99], v85 offset:16384
	ds_read_b128 v[100:103], v85 offset:20480
	s_waitcnt lgkmcnt(0)
	v_mfma_f32_32x32x16_bf16 v[48:63], v[88:91], v[96:99], v[48:63]
	v_mfma_f32_32x32x16_bf16 v[32:47], v[88:91], v[100:103], v[32:47]
	v_mfma_f32_32x32x16_bf16 v[16:31], v[92:95], v[96:99], v[16:31]
	v_mfma_f32_32x32x16_bf16 v[0:15], v[92:95], v[100:103], v[0:15]
	ds_read_b128 v[88:91], v84
	ds_read_b128 v[92:95], v84 offset:4096
	ds_read_b128 v[96:99], v86 offset:16384
	ds_read_b128 v[100:103], v86 offset:20480
	s_waitcnt vmcnt(0)
	s_waitcnt vmcnt(0) lgkmcnt(0)
	s_barrier
; #define MFMA(a, b, c) __builtin_amdgcn_mfma_f32_32x32x16_bf16(a, b, c, 0, 0, 0)
; #define ISSUE(k0, bf) do { char* A_ = lw + (bf) * BUF; \
;     _Pragma("unroll") for (int i_ = 0; i_ < 4; ++i_) { glds16(al.ptr(lrow + 32 * i_, (k0) + cg), A_ + i_ * 4096); glds16(bl.ptr(lrow + 32 * i_, (k0) + cg), A_ + ABYTES + i_ * 4096); } \
;     if (HALO) { if (wid == 0) glds16(gh + (k0), A_ + 16384); } } while (0)
; template <bool HALO, class AL, class BL>
; __device__ __forceinline__ void gemm_core(f32x16 (&acc)[2][2], f32x16& hacc, const AL& al, const BL& bl, int K, char* lds,
;                                           const u16* halo0, const u16* halo1, int brow0, int brow1) {
;     ...
;   for (int kt = 0; kt < nk; ++kt) {
;     asm volatile("s_waitcnt vmcnt(0)" ::: "memory");
;     __syncthreads();
;     if (kt + 1 < nk) ISSUE((kt + 1) * 64, (kt + 1) & 1);
;     const char* T = lds + (kt & 1) * BUF;
; #pragma unroll
;     for (int kk = 0; kk < 4; ++kk) {
;       const int c = kk * 2 + hi;
;       bf16x8 a0 = *(const bf16x8*)(T + oa + ((c ^ sa) << 4));
;       bf16x8 a1 = *(const bf16x8*)(T + oa + 4096 + ((c ^ sa) << 4));
;       bf16x8 b0 = *(const bf16x8*)(T + ob0 + ((c ^ sb0) << 4));
;       bf16x8 b1 = *(const bf16x8*)(T + ob1 + ((c ^ sb1) << 4));
;       acc[0][0] = MFMA(a0, b0, acc[0][0]); acc[0][1] = MFMA(a0, b1, acc[0][1]);
;       acc[1][0] = MFMA(a1, b0, acc[1][0]); acc[1][1] = MFMA(a1, b1, acc[1][1]);
;       if (HALO) { bf16x8 ah = *(const bf16x8*)(T + oh + ((c ^ sh) << 4)); hacc = MFMA(ah, b0, hacc); }
;     }
	v_mfma_f32_32x32x16_bf16 v[48:63], v[88:91], v[96:99], v[48:63]
	v_mfma_f32_32x32x16_bf16 v[32:47], v[88:91], v[100:103], v[32:47]
	v_lshl_add_u64 v[88:89], v[64:65], 0, s[34:35]
	global_load_lds_dwordx4 v[88:89], off
	v_lshl_add_u64 v[88:89], v[66:67], 0, s[34:35]
	s_mov_b32 m0, s70
	v_lshl_add_u64 v[64:65], v[64:65], 0, s[38:39]
	global_load_lds_dwordx4 v[88:89], off
	v_lshl_add_u64 v[88:89], v[68:69], 0, s[34:35]
	s_mov_b32 m0, s71
	v_mfma_f32_32x32x16_bf16 v[16:31], v[92:95], v[96:99], v[16:31]
	global_load_lds_dwordx4 v[88:89], off
	v_lshl_add_u64 v[88:89], v[70:71], 0, s[34:35]
	s_mov_b32 m0, s72
	s_nop 0
	global_load_lds_dwordx4 v[88:89], off
	v_lshl_add_u64 v[88:89], v[72:73], 0, s[34:35]
	s_mov_b32 m0, s41
	v_mfma_f32_32x32x16_bf16 v[0:15], v[92:95], v[100:103], v[0:15]
	global_load_lds_dwordx4 v[88:89], off
	v_lshl_add_u64 v[88:89], v[74:75], 0, s[34:35]
	s_mov_b32 m0, s60
	s_nop 0
	global_load_lds_dwordx4 v[88:89], off
	v_lshl_add_u64 v[88:89], v[76:77], 0, s[34:35]
	s_mov_b32 m0, s64
	s_nop 0
	global_load_lds_dwordx4 v[88:89], off
	v_lshl_add_u64 v[88:89], v[78:79], 0, s[34:35]
	s_mov_b32 m0, s65
	s_nop 0
	global_load_lds_dwordx4 v[88:89], off
	ds_read_b128 v[88:91], v80 offset:32768
	ds_read_b128 v[92:95], v80 offset:36864
	ds_read_b128 v[96:99], v81 offset:49152
	ds_read_b128 v[100:103], v81 offset:53248
	s_waitcnt lgkmcnt(0)
	v_mfma_f32_32x32x16_bf16 v[48:63], v[88:91], v[96:99], v[48:63]
	s_mov_b32 m0, s61
	s_mov_b64 s[60:61], -1
	v_mfma_f32_32x32x16_bf16 v[32:47], v[88:91], v[100:103], v[32:47]
	v_mfma_f32_32x32x16_bf16 v[16:31], v[92:95], v[96:99], v[16:31]
	v_mfma_f32_32x32x16_bf16 v[0:15], v[92:95], v[100:103], v[0:15]
	ds_read_b128 v[88:91], v83 offset:32768
	ds_read_b128 v[92:95], v83 offset:36864
	ds_read_b128 v[96:99], v82 offset:49152
	ds_read_b128 v[100:103], v82 offset:53248
	s_waitcnt lgkmcnt(0)
	v_mfma_f32_32x32x16_bf16 v[48:63], v[88:91], v[96:99], v[48:63]
	v_mfma_f32_32x32x16_bf16 v[32:47], v[88:91], v[100:103], v[32:47]
	v_mfma_f32_32x32x16_bf16 v[16:31], v[92:95], v[96:99], v[16:31]
	v_mfma_f32_32x32x16_bf16 v[0:15], v[92:95], v[100:103], v[0:15]
	ds_read_b128 v[88:91], v87 offset:32768
	ds_read_b128 v[92:95], v87 offset:36864
	ds_read_b128 v[96:99], v85 offset:49152
	ds_read_b128 v[100:103], v85 offset:53248
	s_waitcnt lgkmcnt(0)
	v_mfma_f32_32x32x16_bf16 v[48:63], v[88:91], v[96:99], v[48:63]
	v_mfma_f32_32x32x16_bf16 v[32:47], v[88:91], v[100:103], v[32:47]
	v_mfma_f32_32x32x16_bf16 v[16:31], v[92:95], v[96:99], v[16:31]
	v_mfma_f32_32x32x16_bf16 v[0:15], v[92:95], v[100:103], v[0:15]
	ds_read_b128 v[88:91], v84 offset:32768
	ds_read_b128 v[92:95], v84 offset:36864
	ds_read_b128 v[96:99], v86 offset:49152
	ds_read_b128 v[100:103], v86 offset:53248
	s_waitcnt vmcnt(0)
	s_waitcnt vmcnt(0) lgkmcnt(0)
	s_barrier
	global_load_lds_dwordx4 v[64:65], off
	v_lshl_add_u64 v[64:65], v[66:67], 0, s[38:39]
	s_mov_b32 m0, s63
	v_mfma_f32_32x32x16_bf16 v[48:63], v[88:91], v[96:99], v[48:63]
	global_load_lds_dwordx4 v[64:65], off
	v_lshl_add_u64 v[64:65], v[68:69], 0, s[38:39]
	s_mov_b32 m0, s73
	s_nop 0
	global_load_lds_dwordx4 v[64:65], off
	v_lshl_add_u64 v[64:65], v[70:71], 0, s[38:39]
	s_mov_b32 m0, s80
	v_mfma_f32_32x32x16_bf16 v[32:47], v[88:91], v[100:103], v[32:47]
	global_load_lds_dwordx4 v[64:65], off
	v_lshl_add_u64 v[64:65], v[72:73], 0, s[38:39]
	s_mov_b32 m0, s81
	s_nop 0
	global_load_lds_dwordx4 v[64:65], off
	v_lshl_add_u64 v[64:65], v[74:75], 0, s[38:39]
	s_mov_b32 m0, s82
	v_mfma_f32_32x32x16_bf16 v[16:31], v[92:95], v[96:99], v[16:31]
	global_load_lds_dwordx4 v[64:65], off
	v_lshl_add_u64 v[64:65], v[76:77], 0, s[38:39]
	s_mov_b32 m0, s83
	s_nop 0
	global_load_lds_dwordx4 v[64:65], off
	v_lshl_add_u64 v[64:65], v[78:79], 0, s[38:39]
	s_mov_b32 m0, s84
	v_mfma_f32_32x32x16_bf16 v[0:15], v[92:95], v[100:103], v[0:15]
	global_load_lds_dwordx4 v[64:65], off
	ds_read_b128 v[64:67], v80
	ds_read_b128 v[68:71], v80 offset:4096
	ds_read_b128 v[72:75], v81 offset:16384
	ds_read_b128 v[76:79], v81 offset:20480
	s_waitcnt lgkmcnt(0)
	v_mfma_f32_32x32x16_bf16 v[48:63], v[64:67], v[72:75], v[48:63]
	v_mfma_f32_32x32x16_bf16 v[32:47], v[64:67], v[76:79], v[32:47]
	v_mfma_f32_32x32x16_bf16 v[16:31], v[68:71], v[72:75], v[16:31]
	v_mfma_f32_32x32x16_bf16 v[0:15], v[68:71], v[76:79], v[0:15]
	ds_read_b128 v[64:67], v83
	ds_read_b128 v[68:71], v83 offset:4096
	ds_read_b128 v[72:75], v82 offset:16384
	ds_read_b128 v[76:79], v82 offset:20480
	s_waitcnt lgkmcnt(0)
	v_mfma_f32_32x32x16_bf16 v[48:63], v[64:67], v[72:75], v[48:63]
	v_mfma_f32_32x32x16_bf16 v[32:47], v[64:67], v[76:79], v[32:47]
	v_mfma_f32_32x32x16_bf16 v[16:31], v[68:71], v[72:75], v[16:31]
	v_mfma_f32_32x32x16_bf16 v[0:15], v[68:71], v[76:79], v[0:15]
	ds_read_b128 v[64:67], v87
	ds_read_b128 v[68:71], v87 offset:4096
	ds_read_b128 v[72:75], v85 offset:16384
	ds_read_b128 v[76:79], v85 offset:20480
	s_waitcnt lgkmcnt(0)
	v_mfma_f32_32x32x16_bf16 v[48:63], v[64:67], v[72:75], v[48:63]
	v_mfma_f32_32x32x16_bf16 v[32:47], v[64:67], v[76:79], v[32:47]
	v_mfma_f32_32x32x16_bf16 v[16:31], v[68:71], v[72:75], v[16:31]
	v_mfma_f32_32x32x16_bf16 v[0:15], v[68:71], v[76:79], v[0:15]
	ds_read_b128 v[64:67], v84
	ds_read_b128 v[68:71], v84 offset:4096
	ds_read_b128 v[72:75], v86 offset:16384
	ds_read_b128 v[76:79], v86 offset:20480
	s_waitcnt vmcnt(0)
	s_waitcnt vmcnt(0) lgkmcnt(0)
	s_barrier
; __device__ __forceinline__ float bf2f(u16 v) { return __uint_as_float(((unsigned)v) << 16); }
; __device__ __forceinline__ int opq() { int z = 0; asm volatile("" : "+v"(z)); return z; }
; #define MFMA(a, b, c) __builtin_amdgcn_mfma_f32_32x32x16_bf16(a, b, c, 0, 0, 0)
; template <bool HALO, class AL, class BL>
; __device__ __forceinline__ void gemm_core(f32x16 (&acc)[2][2], f32x16& hacc, const AL& al, const BL& bl, int K, char* lds,
;                                           const u16* halo0, const u16* halo1, int brow0, int brow1) {
;     ...
;     for (int kk = 0; kk < 4; ++kk) {
;       const int c = kk * 2 + hi;
;       bf16x8 a0 = *(const bf16x8*)(T + oa + ((c ^ sa) << 4));
;       bf16x8 a1 = *(const bf16x8*)(T + oa + 4096 + ((c ^ sa) << 4));
;       bf16x8 b0 = *(const bf16x8*)(T + ob0 + ((c ^ sb0) << 4));
;       bf16x8 b1 = *(const bf16x8*)(T + ob1 + ((c ^ sb1) << 4));
;       acc[0][0] = MFMA(a0, b0, acc[0][0]); acc[0][1] = MFMA(a0, b1, acc[0][1]);
;       acc[1][0] = MFMA(a1, b0, acc[1][0]); acc[1][1] = MFMA(a1, b1, acc[1][1]);
;       if (HALO) { bf16x8 ah = *(const bf16x8*)(T + oh + ((c ^ sh) << 4)); hacc = MFMA(ah, b0, hacc); }
;     }
; __device__ __forceinline__ void phase_wout(const P& p, int layer, char* lds) {
;     ...
;     const unsigned rb = (unsigned)(tm * 128 + wr * 64 + 4 * hi + opq());
;     _Float16* pre1 = (_Float16*)(p.ws + OFF_PRE1);
; #pragma unroll
;     for (int mi = 0; mi < 2; ++mi) {
;       float xr[2][16];
;       if (layer == 0) {
; #pragma unroll
;         for (int ni = 0; ni < 2; ++ni)
; #pragma unroll
;           for (int r = 0; r < 16; ++r) xr[ni][r] = p.x[(rb + mi * 32 + (r & 3) + 8 * (r >> 2)) * DM + tn * 128 + wc * 64 + ni * 32 + r32];
;       } else {
; #pragma unroll
;         for (int ni = 0; ni < 2; ++ni)
; #pragma unroll
;           for (int r = 0; r < 16; ++r) xr[ni][r] = bf2f(xbr[(rb + mi * 32 + (r & 3) + 8 * (r >> 2)) * DM + tn * 128 + wc * 64 + ni * 32 + r32]);
;       }
	v_mfma_f32_32x32x16_bf16 v[48:63], v[64:67], v[72:75], v[48:63]
	v_mfma_f32_32x32x16_bf16 v[32:47], v[64:67], v[76:79], v[32:47]
	v_mfma_f32_32x32x16_bf16 v[16:31], v[68:71], v[72:75], v[16:31]
	v_mfma_f32_32x32x16_bf16 v[0:15], v[68:71], v[76:79], v[0:15]
	ds_read_b128 v[64:67], v80 offset:32768
	ds_read_b128 v[68:71], v80 offset:36864
	ds_read_b128 v[72:75], v81 offset:49152
	ds_read_b128 v[76:79], v81 offset:53248
	s_waitcnt lgkmcnt(1)
	v_mfma_f32_32x32x16_bf16 v[48:63], v[64:67], v[72:75], v[48:63]
	s_waitcnt lgkmcnt(0)
	v_mfma_f32_32x32x16_bf16 v[32:47], v[64:67], v[76:79], v[32:47]
	v_mfma_f32_32x32x16_bf16 v[16:31], v[68:71], v[72:75], v[16:31]
	v_mfma_f32_32x32x16_bf16 v[0:15], v[68:71], v[76:79], v[0:15]
	ds_read_b128 v[64:67], v83 offset:32768
	ds_read_b128 v[68:71], v83 offset:36864
	ds_read_b128 v[72:75], v82 offset:49152
	ds_read_b128 v[76:79], v82 offset:53248
	s_waitcnt lgkmcnt(1)
	v_mfma_f32_32x32x16_bf16 v[48:63], v[64:67], v[72:75], v[48:63]
	s_waitcnt lgkmcnt(0)
	v_mfma_f32_32x32x16_bf16 v[32:47], v[64:67], v[76:79], v[32:47]
	v_mfma_f32_32x32x16_bf16 v[16:31], v[68:71], v[72:75], v[16:31]
	v_mfma_f32_32x32x16_bf16 v[0:15], v[68:71], v[76:79], v[0:15]
	ds_read_b128 v[64:67], v87 offset:32768
	ds_read_b128 v[68:71], v87 offset:36864
	ds_read_b128 v[72:75], v85 offset:49152
	ds_read_b128 v[76:79], v85 offset:53248
	s_waitcnt lgkmcnt(1)
	v_mfma_f32_32x32x16_bf16 v[48:63], v[64:67], v[72:75], v[48:63]
	s_waitcnt lgkmcnt(0)
	v_mfma_f32_32x32x16_bf16 v[32:47], v[64:67], v[76:79], v[32:47]
	v_mfma_f32_32x32x16_bf16 v[16:31], v[68:71], v[72:75], v[16:31]
	v_mfma_f32_32x32x16_bf16 v[0:15], v[68:71], v[76:79], v[0:15]
	ds_read_b128 v[64:67], v84 offset:32768
	ds_read_b128 v[68:71], v84 offset:36864
	ds_read_b128 v[72:75], v86 offset:49152
	ds_read_b128 v[76:79], v86 offset:53248
	s_waitcnt lgkmcnt(1)
	v_mfma_f32_32x32x16_bf16 v[48:63], v[64:67], v[72:75], v[48:63]
	s_waitcnt lgkmcnt(0)
	v_mfma_f32_32x32x16_bf16 v[32:47], v[64:67], v[76:79], v[32:47]
	v_mov_b32_e32 v64, v201
	v_lshl_add_u32 v65, s8, 7, v126
	s_nop 0
	v_add_lshl_u32 v129, v65, v64, 10
	v_cndmask_b32_e64 v64, 0, 1, s[76:77]
	v_add_u32_e32 v157, 0x400, v129
	v_mfma_f32_32x32x16_bf16 v[16:31], v[68:71], v[72:75], v[16:31]
	v_add_u32_e32 v156, 0x800, v129
	v_add_u32_e32 v155, 0xc00, v129
	v_add_u32_e32 v153, 0x2000, v129
	v_add_u32_e32 v151, 0x2400, v129
	v_add_u32_e32 v150, 0x2800, v129
	v_add_u32_e32 v149, 0x2c00, v129
	v_add_u32_e32 v146, 0x4000, v129
	v_mfma_f32_32x32x16_bf16 v[0:15], v[68:71], v[76:79], v[0:15]
	v_add_u32_e32 v145, 0x4400, v129
	v_add_u32_e32 v144, 0x4800, v129
	v_add_u32_e32 v142, 0x4c00, v129
	v_add_u32_e32 v141, 0x6000, v129
	v_add_u32_e32 v140, 0x6400, v129
	v_add_u32_e32 v138, 0x6800, v129
	v_add_u32_e32 v137, 0x6c00, v129
	v_add_u32_e32 v200, v129, v128
	v_cmp_ne_u32_e64 s[40:41], 1, v64
	v_add_u32_e32 v90, v157, v128
	v_add_u32_e32 v92, v156, v128
	v_add_u32_e32 v88, v155, v128
	v_add_u32_e32 v86, v153, v128
	v_add_u32_e32 v84, v151, v128
	v_add_u32_e32 v82, v150, v128
	v_add_u32_e32 v80, v149, v128
	v_add_u32_e32 v76, v146, v128
	v_add_u32_e32 v78, v145, v128
	v_add_u32_e32 v74, v144, v128
	v_add_u32_e32 v72, v142, v128
	v_add_u32_e32 v70, v141, v128
	v_add_u32_e32 v68, v140, v128
	v_add_u32_e32 v66, v138, v128
	v_add_u32_e32 v64, v137, v128
	s_cbranch_vccnz .LBB0_242
; __device__ __forceinline__ float bf2f(u16 v) { return __uint_as_float(((unsigned)v) << 16); }
; __device__ __forceinline__ void phase_wout(const P& p, int layer, char* lds) {
;     ...
; #pragma unroll
;         for (int ni = 0; ni < 2; ++ni)
; #pragma unroll
;           for (int r = 0; r < 16; ++r) xr[ni][r] = bf2f(xbr[(rb + mi * 32 + (r & 3) + 8 * (r >> 2)) * DM + tn * 128 + wc * 64 + ni * 32 + r32]);
;       }
	v_lshl_add_u64 v[94:95], v[200:201], 1, s[42:43]
	v_mov_b32_e32 v91, v201
	v_lshl_add_u64 v[96:97], v[90:91], 1, s[42:43]
	global_load_ushort v130, v[94:95], off
	global_load_ushort v131, v[96:97], off
	v_mov_b32_e32 v93, v201
	v_lshl_add_u64 v[94:95], v[92:93], 1, s[42:43]
	v_mov_b32_e32 v89, v201
	v_lshl_add_u64 v[96:97], v[88:89], 1, s[42:43]
	v_mov_b32_e32 v87, v201
	v_mov_b32_e32 v85, v201
	v_mov_b32_e32 v83, v201
	v_mov_b32_e32 v81, v201
	v_mov_b32_e32 v77, v201
	v_mov_b32_e32 v79, v201
	v_mov_b32_e32 v75, v201
	v_mov_b32_e32 v73, v201
	v_mov_b32_e32 v71, v201
	v_mov_b32_e32 v69, v201
	v_or_b32_e32 v168, 32, v128
	v_mov_b32_e32 v205, v179
	v_mov_b32_e32 v217, v181
	s_mov_b64 s[60:61], 0
	global_load_ushort v132, v[94:95], off
	global_load_ushort v133, v[96:97], off
	v_lshl_add_u64 v[94:95], v[86:87], 1, s[42:43]
	v_lshl_add_u64 v[96:97], v[84:85], 1, s[42:43]
	global_load_ushort v134, v[94:95], off
	global_load_ushort v135, v[96:97], off
	v_lshl_add_u64 v[94:95], v[82:83], 1, s[42:43]
	v_lshl_add_u64 v[96:97], v[80:81], 1, s[42:43]
	global_load_ushort v139, v[94:95], off
	global_load_ushort v143, v[96:97], off
	v_lshl_add_u64 v[94:95], v[76:77], 1, s[42:43]
	v_lshl_add_u64 v[96:97], v[78:79], 1, s[42:43]
	global_load_ushort v147, v[94:95], off
	global_load_ushort v148, v[96:97], off
	v_lshl_add_u64 v[94:95], v[74:75], 1, s[42:43]
	v_lshl_add_u64 v[96:97], v[72:73], 1, s[42:43]
	global_load_ushort v152, v[94:95], off
	global_load_ushort v154, v[96:97], off
	v_lshl_add_u64 v[94:95], v[70:71], 1, s[42:43]
	v_lshl_add_u64 v[96:97], v[68:69], 1, s[42:43]
	global_load_ushort v158, v[94:95], off
	global_load_ushort v159, v[96:97], off
	v_mov_b32_e32 v67, v201
	v_lshl_add_u64 v[94:95], v[66:67], 1, s[42:43]
	v_mov_b32_e32 v65, v201
	v_lshl_add_u64 v[96:97], v[64:65], 1, s[42:43]
	global_load_ushort v160, v[94:95], off
	s_nop 0
	global_load_ushort v161, v[96:97], off
	v_add_u32_e32 v96, v157, v168
	v_mov_b32_e32 v97, v201
	v_lshl_add_u64 v[100:101], v[96:97], 1, s[42:43]
	v_add_u32_e32 v94, v129, v168
	v_mov_b32_e32 v95, v201
	v_lshl_add_u64 v[98:99], v[94:95], 1, s[42:43]
	global_load_ushort v163, v[100:101], off
	s_nop 0
	global_load_ushort v162, v[98:99], off
	v_mov_b32_e32 v99, v201
	v_mov_b32_e32 v101, v201
	v_add_u32_e32 v98, v156, v168
	v_lshl_add_u64 v[102:103], v[98:99], 1, s[42:43]
	v_add_u32_e32 v100, v155, v168
	v_lshl_add_u64 v[104:105], v[100:101], 1, s[42:43]
	global_load_ushort v164, v[102:103], off
	s_nop 0
	global_load_ushort v165, v[104:105], off
	v_add_u32_e32 v104, v151, v168
	v_mov_b32_e32 v105, v201
	v_lshl_add_u64 v[108:109], v[104:105], 1, s[42:43]
	v_add_u32_e32 v102, v153, v168
	v_mov_b32_e32 v103, v201
	v_lshl_add_u64 v[106:107], v[102:103], 1, s[42:43]
	global_load_ushort v166, v[106:107], off
	s_nop 0
	global_load_ushort v167, v[108:109], off
	v_add_u32_e32 v108, v149, v168
	v_mov_b32_e32 v109, v201
	v_lshl_add_u64 v[112:113], v[108:109], 1, s[42:43]
	v_add_u32_e32 v106, v150, v168
	v_mov_b32_e32 v107, v201
	v_lshl_add_u64 v[110:111], v[106:107], 1, s[42:43]
	global_load_ushort v169, v[110:111], off
	s_nop 0
	global_load_ushort v170, v[112:113], off
	v_add_u32_e32 v112, v145, v168
	v_mov_b32_e32 v113, v201
	v_lshl_add_u64 v[116:117], v[112:113], 1, s[42:43]
	v_add_u32_e32 v110, v146, v168
	v_mov_b32_e32 v111, v201
	v_lshl_add_u64 v[114:115], v[110:111], 1, s[42:43]
	global_load_ushort v171, v[114:115], off
	s_nop 0
	global_load_ushort v172, v[116:117], off
	v_add_u32_e32 v116, v142, v168
	v_mov_b32_e32 v117, v201
	v_lshl_add_u64 v[120:121], v[116:117], 1, s[42:43]
	v_add_u32_e32 v114, v144, v168
	v_mov_b32_e32 v115, v201
	v_lshl_add_u64 v[118:119], v[114:115], 1, s[42:43]
	global_load_ushort v173, v[118:119], off
	s_nop 0
	global_load_ushort v174, v[120:121], off
	v_add_u32_e32 v120, v140, v168
	v_mov_b32_e32 v121, v201
	v_lshl_add_u64 v[124:125], v[120:121], 1, s[42:43]
	v_add_u32_e32 v118, v141, v168
	v_mov_b32_e32 v119, v201
	v_lshl_add_u64 v[122:123], v[118:119], 1, s[42:43]
	global_load_ushort v175, v[122:123], off
	s_nop 0
	global_load_ushort v176, v[124:125], off
	v_add_u32_e32 v124, v137, v168
	v_mov_b32_e32 v125, v201
	v_lshl_add_u64 v[180:181], v[124:125], 1, s[42:43]
	v_add_u32_e32 v122, v138, v168
	v_mov_b32_e32 v123, v201
	v_lshl_add_u64 v[178:179], v[122:123], 1, s[42:43]
	global_load_ushort v177, v[178:179], off
	v_mov_b32_e32 v179, v205
	global_load_ushort v178, v[180:181], off
	v_mov_b32_e32 v181, v217
	s_waitcnt vmcnt(0)
	v_lshlrev_b32_e32 v130, 16, v130
	v_lshlrev_b32_e32 v131, 16, v131
	v_lshlrev_b32_e32 v132, 16, v132
	v_lshlrev_b32_e32 v133, 16, v133
	v_lshlrev_b32_e32 v134, 16, v134
	v_lshlrev_b32_e32 v135, 16, v135
	v_lshlrev_b32_e32 v139, 16, v139
	v_lshlrev_b32_e32 v143, 16, v143
	v_lshlrev_b32_e32 v147, 16, v147
	v_lshlrev_b32_e32 v148, 16, v148
	v_lshlrev_b32_e32 v152, 16, v152
	v_lshlrev_b32_e32 v154, 16, v154
	v_lshlrev_b32_e32 v158, 16, v158
	v_lshlrev_b32_e32 v159, 16, v159
	v_lshlrev_b32_e32 v160, 16, v160
	v_lshlrev_b32_e32 v161, 16, v161
	v_lshlrev_b32_e32 v163, 16, v163
	v_lshlrev_b32_e32 v162, 16, v162
	v_lshlrev_b32_e32 v164, 16, v164
	v_lshlrev_b32_e32 v165, 16, v165
	v_lshlrev_b32_e32 v166, 16, v166
	v_lshlrev_b32_e32 v167, 16, v167
	v_lshlrev_b32_e32 v169, 16, v169
	v_lshlrev_b32_e32 v170, 16, v170
	v_lshlrev_b32_e32 v171, 16, v171
	v_lshlrev_b32_e32 v172, 16, v172
	v_lshlrev_b32_e32 v173, 16, v173
	v_lshlrev_b32_e32 v174, 16, v174
	v_lshlrev_b32_e32 v175, 16, v175
	v_lshlrev_b32_e32 v176, 16, v176
	v_lshlrev_b32_e32 v177, 16, v177
	v_lshlrev_b32_e32 v178, 16, v178

; #define SBAR() __builtin_amdgcn_sched_barrier(0)
; __device__ __forceinline__ void phase_wout(const P& p, int layer, char* lds) {
;     ...
; #pragma unroll
;       for (int ni = 0; ni < 2; ++ni)
; #pragma unroll
;         for (int r = 0; r < 16; ++r) {
;           const unsigned row = rb + mi * 32 + (r & 3) + 8 * (r >> 2); const unsigned col = tn * 128 + wc * 64 + ni * 32 + r32;
;           pre1[row * DM + col] = (_Float16)(ALPHA * xr[ni][r] + acc[mi][ni][r]);
;         }
;       SBAR();
.LBB0_244:
	s_waitcnt vmcnt(31)
	v_fma_mixlo_f16 v48, v130, s12, v48
	v_lshl_add_u64 v[136:137], v[200:201], 1, s[58:59]
	global_store_short v[136:137], v48, off
	s_waitcnt vmcnt(31)
	v_fma_mixlo_f16 v130, v131, s12, v49
	v_lshl_add_u64 v[48:49], v[90:91], 1, s[58:59]
	global_store_short v[48:49], v130, off
	s_waitcnt vmcnt(31)
	v_fma_mixlo_f16 v50, v132, s12, v50
	v_lshl_add_u64 v[48:49], v[92:93], 1, s[58:59]
	global_store_short v[48:49], v50, off
	s_waitcnt vmcnt(31)
	v_fma_mixlo_f16 v50, v133, s12, v51
	v_lshl_add_u64 v[48:49], v[88:89], 1, s[58:59]
	global_store_short v[48:49], v50, off
	s_waitcnt vmcnt(31)
	v_fma_mixlo_f16 v50, v134, s12, v52
	v_lshl_add_u64 v[48:49], v[86:87], 1, s[58:59]
	global_store_short v[48:49], v50, off
	s_waitcnt vmcnt(31)
	v_fma_mixlo_f16 v50, v135, s12, v53
	v_lshl_add_u64 v[48:49], v[84:85], 1, s[58:59]
	global_store_short v[48:49], v50, off
	s_waitcnt vmcnt(31)
	v_fma_mixlo_f16 v50, v139, s12, v54
	v_lshl_add_u64 v[48:49], v[82:83], 1, s[58:59]
	global_store_short v[48:49], v50, off
	s_waitcnt vmcnt(31)
	v_fma_mixlo_f16 v50, v143, s12, v55
	v_lshl_add_u64 v[48:49], v[80:81], 1, s[58:59]
	global_store_short v[48:49], v50, off
	s_waitcnt vmcnt(31)
	v_fma_mixlo_f16 v50, v147, s12, v56
	v_lshl_add_u64 v[48:49], v[76:77], 1, s[58:59]
	global_store_short v[48:49], v50, off
	s_waitcnt vmcnt(31)
	v_fma_mixlo_f16 v50, v148, s12, v57
	v_lshl_add_u64 v[48:49], v[78:79], 1, s[58:59]
	global_store_short v[48:49], v50, off
	s_waitcnt vmcnt(31)
	v_fma_mixlo_f16 v50, v152, s12, v58
	v_lshl_add_u64 v[48:49], v[74:75], 1, s[58:59]
	global_store_short v[48:49], v50, off
	s_waitcnt vmcnt(31)
	v_fma_mixlo_f16 v50, v154, s12, v59
	v_lshl_add_u64 v[48:49], v[72:73], 1, s[58:59]
	global_store_short v[48:49], v50, off
	s_waitcnt vmcnt(31)
	v_fma_mixlo_f16 v50, v158, s12, v60
	v_lshl_add_u64 v[48:49], v[70:71], 1, s[58:59]
	global_store_short v[48:49], v50, off
	s_waitcnt vmcnt(31)
	v_fma_mixlo_f16 v50, v159, s12, v61
	v_lshl_add_u64 v[48:49], v[68:69], 1, s[58:59]
	global_store_short v[48:49], v50, off
	s_waitcnt vmcnt(31)
	v_fma_mixlo_f16 v50, v160, s12, v62
	v_lshl_add_u64 v[48:49], v[66:67], 1, s[58:59]
	global_store_short v[48:49], v50, off
	s_waitcnt vmcnt(31)
	v_fma_mixlo_f16 v50, v161, s12, v63
	v_lshl_add_u64 v[48:49], v[64:65], 1, s[58:59]
	global_store_short v[48:49], v50, off
	s_waitcnt vmcnt(31)
	v_fma_mixlo_f16 v32, v162, s12, v32
	v_lshl_add_u64 v[48:49], v[94:95], 1, s[58:59]
	global_store_short v[48:49], v32, off
	s_waitcnt vmcnt(31)
	v_fma_mixlo_f16 v48, v163, s12, v33
	v_lshl_add_u64 v[32:33], v[96:97], 1, s[58:59]
	global_store_short v[32:33], v48, off
	s_waitcnt vmcnt(31)
	v_fma_mixlo_f16 v34, v164, s12, v34
	v_lshl_add_u64 v[32:33], v[98:99], 1, s[58:59]
	global_store_short v[32:33], v34, off
	s_waitcnt vmcnt(31)
	v_fma_mixlo_f16 v34, v165, s12, v35
	v_lshl_add_u64 v[32:33], v[100:101], 1, s[58:59]
	global_store_short v[32:33], v34, off
	s_waitcnt vmcnt(31)
	v_fma_mixlo_f16 v34, v166, s12, v36
	v_lshl_add_u64 v[32:33], v[102:103], 1, s[58:59]
	global_store_short v[32:33], v34, off
	s_waitcnt vmcnt(31)
	v_fma_mixlo_f16 v34, v167, s12, v37
	v_lshl_add_u64 v[32:33], v[104:105], 1, s[58:59]
	global_store_short v[32:33], v34, off
	s_waitcnt vmcnt(31)
	v_fma_mixlo_f16 v34, v169, s12, v38
	v_lshl_add_u64 v[32:33], v[106:107], 1, s[58:59]
	global_store_short v[32:33], v34, off
	s_waitcnt vmcnt(31)
	v_fma_mixlo_f16 v34, v170, s12, v39
	v_lshl_add_u64 v[32:33], v[108:109], 1, s[58:59]
	global_store_short v[32:33], v34, off
	s_waitcnt vmcnt(31)
	v_fma_mixlo_f16 v34, v171, s12, v40
	v_lshl_add_u64 v[32:33], v[110:111], 1, s[58:59]
	global_store_short v[32:33], v34, off
	s_waitcnt vmcnt(31)
	v_fma_mixlo_f16 v34, v172, s12, v41
	v_lshl_add_u64 v[32:33], v[112:113], 1, s[58:59]
	global_store_short v[32:33], v34, off
	s_waitcnt vmcnt(31)
	v_fma_mixlo_f16 v34, v173, s12, v42
	v_lshl_add_u64 v[32:33], v[114:115], 1, s[58:59]
	global_store_short v[32:33], v34, off
	s_waitcnt vmcnt(31)
	v_fma_mixlo_f16 v34, v174, s12, v43
	v_lshl_add_u64 v[32:33], v[116:117], 1, s[58:59]
	global_store_short v[32:33], v34, off
	s_waitcnt vmcnt(31)
	v_fma_mixlo_f16 v34, v175, s12, v44
	v_lshl_add_u64 v[32:33], v[118:119], 1, s[58:59]
	global_store_short v[32:33], v34, off
	s_waitcnt vmcnt(31)
	v_fma_mixlo_f16 v34, v176, s12, v45
	v_lshl_add_u64 v[32:33], v[120:121], 1, s[58:59]
	global_store_short v[32:33], v34, off
	s_waitcnt vmcnt(31)
	v_fma_mixlo_f16 v34, v177, s12, v46
	v_lshl_add_u64 v[32:33], v[122:123], 1, s[58:59]
	global_store_short v[32:33], v34, off
	s_waitcnt vmcnt(31)
	v_fma_mixlo_f16 v34, v178, s12, v47
	v_lshl_add_u64 v[32:33], v[124:125], 1, s[58:59]
	global_store_short v[32:33], v34, off
	v_add_u32_e32 v32, 0x8000, v129
	v_add_u32_e32 v33, 0x8400, v129
	v_add_u32_e32 v34, 0x8800, v129
	v_add_u32_e32 v35, 0x8c00, v129
	v_add_u32_e32 v36, 0xa000, v129
	v_add_u32_e32 v37, 0xa400, v129
	v_add_u32_e32 v38, 0xa800, v129
	v_add_u32_e32 v39, 0xac00, v129
	v_add_u32_e32 v40, 0xc000, v129
	v_add_u32_e32 v41, 0xc400, v129
	v_add_u32_e32 v42, 0xc800, v129
	v_add_u32_e32 v43, 0xcc00, v129
	v_add_u32_e32 v45, 0xe000, v129
	v_add_u32_e32 v47, 0xe400, v129
	v_add_u32_e32 v49, 0xe800, v129
	v_add_u32_e32 v51, 0xec00, v129
	v_add_u32_e32 v200, v32, v128
	s_mov_b64 s[60:61], -1
	s_and_b64 vcc, exec, s[40:41]
	v_add_u32_e32 v48, v168, v32
	v_add_u32_e32 v92, v33, v128
	v_add_u32_e32 v90, v34, v128
	v_add_u32_e32 v88, v35, v128
	v_add_u32_e32 v86, v36, v128
	v_add_u32_e32 v84, v37, v128
	v_add_u32_e32 v82, v38, v128
	v_add_u32_e32 v80, v39, v128
	v_add_u32_e32 v78, v40, v128
	v_add_u32_e32 v76, v41, v128
	v_add_u32_e32 v74, v42, v128
	v_add_u32_e32 v72, v43, v128
	v_add_u32_e32 v70, v45, v128
	v_add_u32_e32 v68, v47, v128
	v_add_u32_e32 v66, v49, v128
	v_add_u32_e32 v64, v51, v128
	v_add_u32_e32 v62, v168, v33
	v_add_u32_e32 v60, v168, v34
	v_add_u32_e32 v58, v168, v35
	v_add_u32_e32 v56, v168, v36
	v_add_u32_e32 v54, v168, v37
	v_add_u32_e32 v52, v168, v38
	v_add_u32_e32 v50, v168, v39
	v_add_u32_e32 v46, v168, v40
	v_add_u32_e32 v44, v168, v41
	v_add_u32_e32 v42, v168, v42
	v_add_u32_e32 v40, v168, v43
	v_add_u32_e32 v38, v168, v45
	v_add_u32_e32 v36, v168, v47
	v_add_u32_e32 v34, v168, v49
	v_add_u32_e32 v32, v168, v51
	s_cbranch_vccnz .LBB0_246
; __device__ __forceinline__ float bf2f(u16 v) { return __uint_as_float(((unsigned)v) << 16); }
; __device__ __forceinline__ void phase_wout(const P& p, int layer, char* lds) {
;     ...
; #pragma unroll
;         for (int ni = 0; ni < 2; ++ni)
; #pragma unroll
;           for (int r = 0; r < 16; ++r) xr[ni][r] = bf2f(xbr[(rb + mi * 32 + (r & 3) + 8 * (r >> 2)) * DM + tn * 128 + wc * 64 + ni * 32 + r32]);
;       }
	v_lshl_add_u64 v[94:95], v[200:201], 1, s[42:43]
	v_mov_b32_e32 v93, v201
	v_lshl_add_u64 v[96:97], v[92:93], 1, s[42:43]
	global_load_ushort v94, v[94:95], off
	global_load_ushort v95, v[96:97], off
	v_mov_b32_e32 v91, v201
	v_lshl_add_u64 v[96:97], v[90:91], 1, s[42:43]
	v_mov_b32_e32 v89, v201
	v_lshl_add_u64 v[98:99], v[88:89], 1, s[42:43]
	v_mov_b32_e32 v87, v201
	v_mov_b32_e32 v85, v201
	v_lshl_add_u64 v[100:101], v[84:85], 1, s[42:43]
	v_mov_b32_e32 v83, v201
	v_mov_b32_e32 v81, v201
	v_lshl_add_u64 v[102:103], v[80:81], 1, s[42:43]
	v_mov_b32_e32 v79, v201
	v_mov_b32_e32 v77, v201
	v_lshl_add_u64 v[104:105], v[76:77], 1, s[42:43]
	v_mov_b32_e32 v75, v201
	v_mov_b32_e32 v73, v201
	v_lshl_add_u64 v[106:107], v[72:73], 1, s[42:43]
	v_mov_b32_e32 v71, v201
	v_mov_b32_e32 v69, v201
	v_lshl_add_u64 v[108:109], v[68:69], 1, s[42:43]
	v_mov_b32_e32 v67, v201
	v_mov_b32_e32 v65, v201
	v_lshl_add_u64 v[110:111], v[64:65], 1, s[42:43]
	v_mov_b32_e32 v49, v201
	v_mov_b32_e32 v63, v201
	v_lshl_add_u64 v[112:113], v[62:63], 1, s[42:43]
	v_mov_b32_e32 v61, v201
	v_mov_b32_e32 v59, v201
	v_lshl_add_u64 v[114:115], v[58:59], 1, s[42:43]
	v_mov_b32_e32 v57, v201
	v_mov_b32_e32 v55, v201
	v_lshl_add_u64 v[116:117], v[54:55], 1, s[42:43]
	v_mov_b32_e32 v53, v201
	v_mov_b32_e32 v51, v201
	v_lshl_add_u64 v[118:119], v[50:51], 1, s[42:43]
	v_mov_b32_e32 v47, v201
	v_mov_b32_e32 v45, v201
	v_lshl_add_u64 v[120:121], v[44:45], 1, s[42:43]
	v_mov_b32_e32 v43, v201
	v_mov_b32_e32 v41, v201
	v_lshl_add_u64 v[122:123], v[40:41], 1, s[42:43]
	v_mov_b32_e32 v39, v201
	v_mov_b32_e32 v37, v201
	v_lshl_add_u64 v[124:125], v[36:37], 1, s[42:43]
	s_mov_b64 s[60:61], 0
	global_load_ushort v96, v[96:97], off
	global_load_ushort v97, v[98:99], off
	v_lshl_add_u64 v[98:99], v[86:87], 1, s[42:43]
	global_load_ushort v98, v[98:99], off
	global_load_ushort v99, v[100:101], off
	v_lshl_add_u64 v[100:101], v[82:83], 1, s[42:43]
	global_load_ushort v100, v[100:101], off
	global_load_ushort v101, v[102:103], off
	v_lshl_add_u64 v[102:103], v[78:79], 1, s[42:43]
	global_load_ushort v102, v[102:103], off
	global_load_ushort v103, v[104:105], off
	v_lshl_add_u64 v[104:105], v[74:75], 1, s[42:43]
	global_load_ushort v104, v[104:105], off
	global_load_ushort v105, v[106:107], off
	v_lshl_add_u64 v[106:107], v[70:71], 1, s[42:43]
	global_load_ushort v106, v[106:107], off
	global_load_ushort v107, v[108:109], off
	v_lshl_add_u64 v[108:109], v[66:67], 1, s[42:43]
	global_load_ushort v108, v[108:109], off
	global_load_ushort v109, v[110:111], off
	v_lshl_add_u64 v[110:111], v[48:49], 1, s[42:43]
	global_load_ushort v110, v[110:111], off
	global_load_ushort v111, v[112:113], off
	v_lshl_add_u64 v[112:113], v[60:61], 1, s[42:43]
	global_load_ushort v112, v[112:113], off
	global_load_ushort v113, v[114:115], off
	v_lshl_add_u64 v[114:115], v[56:57], 1, s[42:43]
	global_load_ushort v114, v[114:115], off
	global_load_ushort v115, v[116:117], off
	v_lshl_add_u64 v[116:117], v[52:53], 1, s[42:43]
	global_load_ushort v116, v[116:117], off
	global_load_ushort v117, v[118:119], off
	v_lshl_add_u64 v[118:119], v[46:47], 1, s[42:43]
	global_load_ushort v118, v[118:119], off
	global_load_ushort v119, v[120:121], off
	v_lshl_add_u64 v[120:121], v[42:43], 1, s[42:43]
	global_load_ushort v120, v[120:121], off
	global_load_ushort v121, v[122:123], off
	v_lshl_add_u64 v[122:123], v[38:39], 1, s[42:43]
	global_load_ushort v122, v[122:123], off
	global_load_ushort v123, v[124:125], off
	v_mov_b32_e32 v35, v201
	v_lshl_add_u64 v[124:125], v[34:35], 1, s[42:43]
	v_mov_b32_e32 v33, v201
	v_lshl_add_u64 v[128:129], v[32:33], 1, s[42:43]
	global_load_ushort v124, v[124:125], off
	s_nop 0
	global_load_ushort v125, v[128:129], off
	s_waitcnt vmcnt(0)
	v_lshlrev_b32_e32 v94, 16, v94
	v_lshlrev_b32_e32 v95, 16, v95
	v_lshlrev_b32_e32 v96, 16, v96
	v_lshlrev_b32_e32 v97, 16, v97
	v_lshlrev_b32_e32 v98, 16, v98
	v_lshlrev_b32_e32 v99, 16, v99
	v_lshlrev_b32_e32 v100, 16, v100
	v_lshlrev_b32_e32 v101, 16, v101
	v_lshlrev_b32_e32 v102, 16, v102
	v_lshlrev_b32_e32 v103, 16, v103
	v_lshlrev_b32_e32 v104, 16, v104
	v_lshlrev_b32_e32 v105, 16, v105
	v_lshlrev_b32_e32 v106, 16, v106
	v_lshlrev_b32_e32 v107, 16, v107
	v_lshlrev_b32_e32 v108, 16, v108
	v_lshlrev_b32_e32 v109, 16, v109
	v_lshlrev_b32_e32 v110, 16, v110
	v_lshlrev_b32_e32 v111, 16, v111
	v_lshlrev_b32_e32 v112, 16, v112
	v_lshlrev_b32_e32 v113, 16, v113
	v_lshlrev_b32_e32 v114, 16, v114
	v_lshlrev_b32_e32 v115, 16, v115
	v_lshlrev_b32_e32 v116, 16, v116
	v_lshlrev_b32_e32 v117, 16, v117
	v_lshlrev_b32_e32 v118, 16, v118
	v_lshlrev_b32_e32 v119, 16, v119
	v_lshlrev_b32_e32 v120, 16, v120
	v_lshlrev_b32_e32 v121, 16, v121
	v_lshlrev_b32_e32 v122, 16, v122
	v_lshlrev_b32_e32 v123, 16, v123
	v_lshlrev_b32_e32 v124, 16, v124
	v_lshlrev_b32_e32 v125, 16, v125
